# v29 + prologue weight transposes: both 16-load batches of an item issued together (32 loads in flight per wave)
# baseline (speedup 1.0000x reference)
; #define LAS __attribute__((address_space(3)))
; __device__ __forceinline__ void transpose_item(const float* W, int K, int N, bf16_t* WT, LAS float* scr, int item, int lane, int perm_cols) {
;     const int nblk = N / 32, kb = item / nblk, nb = item % nblk, k0 = 64 * kb, n0 = 32 * nb;
; #pragma unroll 8
;     for (int i = 0; i < 32; ++i) { const int kk = 2 * i + (lane >> 5); scr[kk * 33 + (lane & 31)] = W[(size_t)(k0 + kk) * N + n0 + (lane & 31)]; }
.LBB0_44:
	v_mov_b32_e32 v173, v5
	s_lshl_b32 s44, s41, 1
	s_lshl_b32 s45, s42, 1
	v_or_b32_e32 v172, s45, v16
	s_add_i32 s46, s44, 4
	s_add_i32 s47, s45, 4
	v_mov_b32_e32 v127, v5
	s_add_i32 s51, s45, 8
	v_lshlrev_b64 v[140:141], 12, v[172:173]
	v_or_b32_e32 v126, s46, v3
	v_or_b32_e32 v172, s47, v16
	v_mov_b32_e32 v125, v5
	v_or_b32_e32 v124, s44, v3
	s_add_i32 s55, s45, 12
	v_lshlrev_b64 v[126:127], 12, v[126:127]
	v_lshlrev_b64 v[142:143], 12, v[172:173]
	v_or_b32_e32 v172, s51, v16
	s_add_i32 s50, s44, 8
	s_add_i32 s54, s44, 12
	s_add_i32 s57, s45, 16
	v_lshlrev_b64 v[124:125], 12, v[124:125]
	v_lshl_add_u64 v[140:141], v[14:15], 0, v[140:141]
	v_lshl_add_u64 v[126:127], v[14:15], 0, v[126:127]
	v_lshlrev_b64 v[144:145], 12, v[172:173]
	v_or_b32_e32 v172, s55, v16
	v_mov_b32_e32 v129, v5
	v_mov_b32_e32 v131, v5
	s_add_i32 s59, s45, 20
	v_or_b32_e32 v128, s50, v3
	v_or_b32_e32 v130, s54, v3
	v_lshl_add_u64 v[124:125], v[14:15], 0, v[124:125]
	v_lshl_add_u64 v[142:143], v[14:15], 0, v[142:143]
	global_load_dword v123, v[140:141], off
	global_load_dword v156, v[124:125], off
	global_load_dword v157, v[142:143], off
	global_load_dword v158, v[126:127], off
	v_lshlrev_b64 v[126:127], 12, v[172:173]
	v_or_b32_e32 v172, s57, v16
	s_add_i32 s56, s44, 16
	s_add_i32 s58, s44, 20
	s_add_i32 s65, s45, 24
	v_lshlrev_b64 v[128:129], 12, v[128:129]
	v_lshlrev_b64 v[130:131], 12, v[130:131]
	v_lshl_add_u64 v[124:125], v[14:15], 0, v[144:145]
	v_lshl_add_u64 v[126:127], v[14:15], 0, v[126:127]
	v_lshlrev_b64 v[140:141], 12, v[172:173]
	v_or_b32_e32 v172, s59, v16
	v_mov_b32_e32 v133, v5
	v_mov_b32_e32 v135, v5
	s_add_i32 s64, s44, 24
	s_add_i32 s66, s44, 28
	s_add_i32 s67, s45, 28
	v_or_b32_e32 v132, s56, v3
	v_or_b32_e32 v134, s58, v3
	v_lshl_add_u64 v[128:129], v[14:15], 0, v[128:129]
	v_lshl_add_u64 v[130:131], v[14:15], 0, v[130:131]
	global_load_dword v159, v[124:125], off
	global_load_dword v160, v[128:129], off
	global_load_dword v161, v[126:127], off
	global_load_dword v162, v[130:131], off
	v_lshlrev_b64 v[126:127], 12, v[172:173]
	v_or_b32_e32 v172, s65, v16
	v_mov_b32_e32 v137, v5
	v_mov_b32_e32 v139, v5
	v_or_b32_e32 v136, s64, v3
	v_or_b32_e32 v138, s66, v3
	v_lshlrev_b64 v[132:133], 12, v[132:133]
	v_lshlrev_b64 v[134:135], 12, v[134:135]
	v_lshl_add_u64 v[124:125], v[14:15], 0, v[140:141]
	v_lshl_add_u64 v[126:127], v[14:15], 0, v[126:127]
	v_lshlrev_b64 v[128:129], 12, v[172:173]
	v_or_b32_e32 v172, s67, v16
	v_lshlrev_b64 v[136:137], 12, v[136:137]
	v_lshlrev_b64 v[138:139], 12, v[138:139]
	v_lshl_add_u64 v[132:133], v[14:15], 0, v[132:133]
	v_lshl_add_u64 v[134:135], v[14:15], 0, v[134:135]
	global_load_dword v163, v[124:125], off
	global_load_dword v164, v[132:133], off
	global_load_dword v165, v[126:127], off
	global_load_dword v166, v[134:135], off
	v_lshl_add_u64 v[124:125], v[14:15], 0, v[128:129]
	v_lshlrev_b64 v[126:127], 12, v[172:173]
	v_lshl_add_u64 v[136:137], v[14:15], 0, v[136:137]
	v_lshl_add_u64 v[138:139], v[14:15], 0, v[138:139]
	v_lshl_add_u64 v[126:127], v[14:15], 0, v[126:127]
	global_load_dword v172, v[124:125], off
	global_load_dword v167, v[136:137], off
	global_load_dword v168, v[126:127], off
	global_load_dword v169, v[138:139], off
	v_or_b32_e32 v126, s44, v1
	v_or_b32_e32 v124, s45, v2
	s_add_i32 s42, s42, 16
	s_add_i32 s41, s41, 16
	s_add_i32 s43, s43, -16
	v_mad_u64_u32 v[124:125], s[44:45], v124, s3, v[6:7]
	v_mad_u64_u32 v[126:127], s[44:45], v126, s3, v[6:7]
	v_or_b32_e32 v125, s46, v1
	v_or_b32_e32 v127, s47, v2
	v_or_b32_e32 v134, s50, v1
	v_or_b32_e32 v132, s51, v2
	v_or_b32_e32 v138, s54, v1
	v_or_b32_e32 v136, s55, v2
	v_or_b32_e32 v142, s56, v1
	v_or_b32_e32 v140, s57, v2
	v_or_b32_e32 v146, s58, v1
	v_or_b32_e32 v144, s59, v2
	v_or_b32_e32 v150, s64, v1
	v_or_b32_e32 v148, s65, v2
	v_or_b32_e32 v154, s66, v1
	v_or_b32_e32 v152, s67, v2
	s_cmp_lg_u32 s43, 0
	v_mad_u64_u32 v[128:129], s[44:45], v127, s3, v[6:7]
	v_mad_u64_u32 v[130:131], s[44:45], v125, s3, v[6:7]
	v_mad_u64_u32 v[132:133], s[44:45], v132, s3, v[6:7]
	v_mad_u64_u32 v[134:135], s[44:45], v134, s3, v[6:7]
	v_mad_u64_u32 v[136:137], s[44:45], v136, s3, v[6:7]
	v_mad_u64_u32 v[138:139], s[44:45], v138, s3, v[6:7]
	v_mad_u64_u32 v[140:141], s[44:45], v140, s3, v[6:7]
	v_mad_u64_u32 v[142:143], s[44:45], v142, s3, v[6:7]
	v_mad_u64_u32 v[144:145], s[44:45], v144, s3, v[6:7]
	v_mad_u64_u32 v[146:147], s[44:45], v146, s3, v[6:7]
	v_mad_u64_u32 v[148:149], s[44:45], v148, s3, v[6:7]
	v_mad_u64_u32 v[150:151], s[44:45], v150, s3, v[6:7]
	v_mad_u64_u32 v[152:153], s[44:45], v152, s3, v[6:7]
	v_mad_u64_u32 v[154:155], s[44:45], v154, s3, v[6:7]
	s_lshl_b32 s44, s41, 1
	s_lshl_b32 s45, s42, 1
	v_or_b32_e32 v4, s45, v16
	s_add_i32 s46, s44, 4
	s_add_i32 s47, s45, 4
	v_mov_b32_e32 v33, v5
	s_add_i32 s51, s45, 8
	v_lshlrev_b64 v[46:47], 12, v[4:5]
	v_or_b32_e32 v32, s46, v3
	v_or_b32_e32 v4, s47, v16
	v_mov_b32_e32 v31, v5
	v_or_b32_e32 v30, s44, v3
	s_add_i32 s55, s45, 12
	v_lshlrev_b64 v[32:33], 12, v[32:33]
	v_lshlrev_b64 v[48:49], 12, v[4:5]
	v_or_b32_e32 v4, s51, v16
	s_add_i32 s50, s44, 8
	s_add_i32 s54, s44, 12
	s_add_i32 s57, s45, 16
	v_lshlrev_b64 v[30:31], 12, v[30:31]
	v_lshl_add_u64 v[46:47], v[14:15], 0, v[46:47]
	v_lshl_add_u64 v[32:33], v[14:15], 0, v[32:33]
	v_lshlrev_b64 v[50:51], 12, v[4:5]
	v_or_b32_e32 v4, s55, v16
	v_mov_b32_e32 v35, v5
	v_mov_b32_e32 v37, v5
	s_add_i32 s59, s45, 20
	v_or_b32_e32 v34, s50, v3
	v_or_b32_e32 v36, s54, v3
	v_lshl_add_u64 v[30:31], v[14:15], 0, v[30:31]
	v_lshl_add_u64 v[48:49], v[14:15], 0, v[48:49]
	global_load_dword v9, v[46:47], off
	global_load_dword v62, v[30:31], off
; __device__ __forceinline__ void transpose_item(const float* W, int K, int N, bf16_t* WT, LAS float* scr, int item, int lane, int perm_cols) {
;     const int nblk = N / 32, kb = item / nblk, nb = item % nblk, k0 = 64 * kb, n0 = 32 * nb;
; #pragma unroll 8
;     for (int i = 0; i < 32; ++i) { const int kk = 2 * i + (lane >> 5); scr[kk * 33 + (lane & 31)] = W[(size_t)(k0 + kk) * N + n0 + (lane & 31)]; }
	global_load_dword v63, v[48:49], off
	global_load_dword v64, v[32:33], off
	v_lshlrev_b64 v[32:33], 12, v[4:5]
	v_or_b32_e32 v4, s57, v16
	s_add_i32 s56, s44, 16
	s_add_i32 s58, s44, 20
	s_add_i32 s65, s45, 24
	v_lshlrev_b64 v[34:35], 12, v[34:35]
	v_lshlrev_b64 v[36:37], 12, v[36:37]
	v_lshl_add_u64 v[30:31], v[14:15], 0, v[50:51]
	v_lshl_add_u64 v[32:33], v[14:15], 0, v[32:33]
	v_lshlrev_b64 v[46:47], 12, v[4:5]
	v_or_b32_e32 v4, s59, v16
	v_mov_b32_e32 v39, v5
	v_mov_b32_e32 v41, v5
	s_add_i32 s64, s44, 24
	s_add_i32 s66, s44, 28
	s_add_i32 s67, s45, 28
	v_or_b32_e32 v38, s56, v3
	v_or_b32_e32 v40, s58, v3
	v_lshl_add_u64 v[34:35], v[14:15], 0, v[34:35]
	v_lshl_add_u64 v[36:37], v[14:15], 0, v[36:37]
	global_load_dword v65, v[30:31], off
	global_load_dword v66, v[34:35], off
	global_load_dword v67, v[32:33], off
	global_load_dword v68, v[36:37], off
	v_lshlrev_b64 v[32:33], 12, v[4:5]
	v_or_b32_e32 v4, s65, v16
	v_mov_b32_e32 v43, v5
	v_mov_b32_e32 v45, v5
	v_or_b32_e32 v42, s64, v3
	v_or_b32_e32 v44, s66, v3
	v_lshlrev_b64 v[38:39], 12, v[38:39]
	v_lshlrev_b64 v[40:41], 12, v[40:41]
	v_lshl_add_u64 v[30:31], v[14:15], 0, v[46:47]
	v_lshl_add_u64 v[32:33], v[14:15], 0, v[32:33]
	v_lshlrev_b64 v[34:35], 12, v[4:5]
	v_or_b32_e32 v4, s67, v16
	v_lshlrev_b64 v[42:43], 12, v[42:43]
	v_lshlrev_b64 v[44:45], 12, v[44:45]
	v_lshl_add_u64 v[38:39], v[14:15], 0, v[38:39]
	v_lshl_add_u64 v[40:41], v[14:15], 0, v[40:41]
	global_load_dword v69, v[30:31], off
	global_load_dword v70, v[38:39], off
	global_load_dword v71, v[32:33], off
	global_load_dword v72, v[40:41], off
	v_lshl_add_u64 v[30:31], v[14:15], 0, v[34:35]
	v_lshlrev_b64 v[32:33], 12, v[4:5]
	v_lshl_add_u64 v[42:43], v[14:15], 0, v[42:43]
	v_lshl_add_u64 v[44:45], v[14:15], 0, v[44:45]
	v_lshl_add_u64 v[32:33], v[14:15], 0, v[32:33]
	global_load_dword v4, v[30:31], off
	global_load_dword v73, v[42:43], off
	global_load_dword v74, v[32:33], off
	global_load_dword v75, v[44:45], off
	v_or_b32_e32 v32, s44, v1
	v_or_b32_e32 v30, s45, v2
	s_add_i32 s42, s42, 16
	s_add_i32 s41, s41, 16
	s_add_i32 s43, s43, -16
	v_mad_u64_u32 v[30:31], s[44:45], v30, s3, v[6:7]
	v_mad_u64_u32 v[32:33], s[44:45], v32, s3, v[6:7]
	v_or_b32_e32 v31, s46, v1
	v_or_b32_e32 v33, s47, v2
	v_or_b32_e32 v40, s50, v1
	v_or_b32_e32 v38, s51, v2
	v_or_b32_e32 v44, s54, v1
	v_or_b32_e32 v42, s55, v2
	v_or_b32_e32 v48, s56, v1
	v_or_b32_e32 v46, s57, v2
	v_or_b32_e32 v52, s58, v1
	v_or_b32_e32 v50, s59, v2
	v_or_b32_e32 v56, s64, v1
	v_or_b32_e32 v54, s65, v2
	v_or_b32_e32 v60, s66, v1
	v_or_b32_e32 v58, s67, v2
	s_cmp_lg_u32 s43, 0
	v_mad_u64_u32 v[34:35], s[44:45], v33, s3, v[6:7]
	v_mad_u64_u32 v[36:37], s[44:45], v31, s3, v[6:7]
	v_mad_u64_u32 v[38:39], s[44:45], v38, s3, v[6:7]
	v_mad_u64_u32 v[40:41], s[44:45], v40, s3, v[6:7]
	v_mad_u64_u32 v[42:43], s[44:45], v42, s3, v[6:7]
	v_mad_u64_u32 v[44:45], s[44:45], v44, s3, v[6:7]
	v_mad_u64_u32 v[46:47], s[44:45], v46, s3, v[6:7]
	v_mad_u64_u32 v[48:49], s[44:45], v48, s3, v[6:7]
	v_mad_u64_u32 v[50:51], s[44:45], v50, s3, v[6:7]
	v_mad_u64_u32 v[52:53], s[44:45], v52, s3, v[6:7]
	v_mad_u64_u32 v[54:55], s[44:45], v54, s3, v[6:7]
	v_mad_u64_u32 v[56:57], s[44:45], v56, s3, v[6:7]
	v_mad_u64_u32 v[58:59], s[44:45], v58, s3, v[6:7]
	v_mad_u64_u32 v[60:61], s[44:45], v60, s3, v[6:7]
	s_waitcnt vmcnt(31)
	ds_write_b32 v124, v123
	s_waitcnt vmcnt(30)
	ds_write_b32 v126, v156
	s_waitcnt vmcnt(29)
	ds_write_b32 v128, v157
	s_waitcnt vmcnt(28)
	ds_write_b32 v130, v158
	s_waitcnt vmcnt(27)
	ds_write_b32 v132, v159
	s_waitcnt vmcnt(26)
; #define LAS __attribute__((address_space(3)))
; __device__ __forceinline__ unsigned cvt_pk_bf16(float lo, float hi) { f32x2 v = {lo, hi}; bf16x2_t b = __builtin_convertvector(v, bf16x2_t); return __builtin_bit_cast(unsigned, b); }
; __device__ __forceinline__ void transpose_item(const float* W, int K, int N, bf16_t* WT, LAS float* scr, int item, int lane, int perm_cols) {
;     ...
;     for (int i = 0; i < 32; ++i) { const int kk = 2 * i + (lane >> 5); scr[kk * 33 + (lane & 31)] = W[(size_t)(k0 + kk) * N + n0 + (lane & 31)]; }
;     asm volatile("s_waitcnt lgkmcnt(0)" ::: "memory");
;     const int c = lane & 7; const bool perm = n0 < perm_cols;
; #pragma unroll
;     for (int j = 0; j < 4; ++j) { const int n = (lane >> 3) + 8 * j; const int sn = perm ? ((n >> 1) + 16 * (n & 1)) : n; const LAS float* s = scr + (8 * c) * 33 + sn;
;         u32x4 o; o.x = cvt_pk_bf16(s[0 * 33], s[1 * 33]); o.y = cvt_pk_bf16(s[2 * 33], s[3 * 33]); o.z = cvt_pk_bf16(s[4 * 33], s[5 * 33]); o.w = cvt_pk_bf16(s[6 * 33], s[7 * 33]);
;         *(u32x4*)(WT + (size_t)(n0 + n) * K + k0 + 8 * c) = o; }
;     asm volatile("s_waitcnt lgkmcnt(0)" ::: "memory");
	ds_write_b32 v134, v160
	s_waitcnt vmcnt(25)
	ds_write_b32 v136, v161
	s_waitcnt vmcnt(24)
	ds_write_b32 v138, v162
	s_waitcnt vmcnt(23)
	ds_write_b32 v140, v163
	s_waitcnt vmcnt(22)
	ds_write_b32 v142, v164
	s_waitcnt vmcnt(21)
	ds_write_b32 v144, v165
	s_waitcnt vmcnt(20)
	ds_write_b32 v146, v166
	s_waitcnt vmcnt(19)
	ds_write_b32 v148, v172
	s_waitcnt vmcnt(18)
	ds_write_b32 v150, v167
	s_waitcnt vmcnt(17)
	ds_write_b32 v152, v168
	s_waitcnt vmcnt(16)
	ds_write_b32 v154, v169
	s_waitcnt vmcnt(15)
	ds_write_b32 v30, v9
	s_waitcnt vmcnt(14)
	ds_write_b32 v32, v62
	s_waitcnt vmcnt(13)
	ds_write_b32 v34, v63
	s_waitcnt vmcnt(12)
	ds_write_b32 v36, v64
	s_waitcnt vmcnt(11)
	ds_write_b32 v38, v65
	s_waitcnt vmcnt(10)
	ds_write_b32 v40, v66
	s_waitcnt vmcnt(9)
	ds_write_b32 v42, v67
	s_waitcnt vmcnt(8)
	ds_write_b32 v44, v68
	s_waitcnt vmcnt(7)
	ds_write_b32 v46, v69
	s_waitcnt vmcnt(6)
	ds_write_b32 v48, v70
	s_waitcnt vmcnt(5)
	ds_write_b32 v50, v71
	s_waitcnt vmcnt(4)
	ds_write_b32 v52, v72
	s_waitcnt vmcnt(3)
	ds_write_b32 v54, v4
	s_waitcnt vmcnt(2)
	ds_write_b32 v56, v73
	s_waitcnt vmcnt(1)
	ds_write_b32 v58, v74
	s_waitcnt vmcnt(0)
	ds_write_b32 v60, v75
	s_waitcnt lgkmcnt(0)
	ds_read2_b32 v[30:31], v20 offset0:33 offset1:41
	ds_read2_b32 v[32:33], v20 offset1:8
	ds_read2_b32 v[34:35], v20 offset0:66 offset1:74
	ds_read2_b32 v[36:37], v20 offset0:99 offset1:107
	ds_read2_b32 v[38:39], v20 offset0:132 offset1:140
	ds_read2_b32 v[40:41], v20 offset0:165 offset1:173
	ds_read2_b32 v[42:43], v20 offset0:198 offset1:206
	ds_read2_b32 v[44:45], v20 offset0:231 offset1:239
	v_lshlrev_b64 v[12:13], 23, v[12:13]
	v_lshl_add_u64 v[12:13], s[4:5], 0, v[12:13]
	v_lshlrev_b32_e32 v4, 1, v11
	v_lshl_add_u64 v[12:13], v[12:13], 0, v[4:5]
	v_mov_b32_e32 v11, v5
	v_or_b32_e32 v3, v17, v18
	v_lshl_add_u64 v[46:47], v[12:13], 0, v[10:11]
	v_lshlrev_b32_e32 v4, 13, v3
	s_waitcnt lgkmcnt(6)
	v_cvt_pk_bf16_f32 v12, v32, v30
	s_waitcnt lgkmcnt(4)
	v_cvt_pk_bf16_f32 v13, v34, v36
	s_waitcnt lgkmcnt(2)
	v_cvt_pk_bf16_f32 v14, v38, v40
	s_waitcnt lgkmcnt(0)
	v_cvt_pk_bf16_f32 v15, v42, v44
	v_lshl_add_u64 v[48:49], v[46:47], 0, v[4:5]
	global_store_dwordx4 v[48:49], v[12:15], off
	v_or_b32_e32 v3, v17, v21
	v_lshlrev_b32_e32 v4, 13, v3
	v_cvt_pk_bf16_f32 v12, v33, v31
	v_cvt_pk_bf16_f32 v13, v35, v37
	v_cvt_pk_bf16_f32 v14, v39, v41
	v_cvt_pk_bf16_f32 v15, v43, v45
	ds_read2_b32 v[32:33], v20 offset0:49 offset1:57
	ds_read2_b32 v[34:35], v20 offset0:16 offset1:24
	ds_read2_b32 v[36:37], v20 offset0:82 offset1:90
	ds_read2_b32 v[38:39], v20 offset0:115 offset1:123
	ds_read2_b32 v[40:41], v20 offset0:148 offset1:156
	ds_read2_b32 v[42:43], v20 offset0:181 offset1:189
	ds_read2_b32 v[44:45], v20 offset0:214 offset1:222
	ds_read2_b32 v[48:49], v20 offset0:247 offset1:255
	v_or_b32_e32 v3, v17, v22
	v_lshl_add_u64 v[30:31], v[46:47], 0, v[4:5]
	v_lshlrev_b32_e32 v4, 13, v3
	v_or_b32_e32 v3, v17, v23
	global_store_dwordx4 v[30:31], v[12:15], off
	v_lshl_add_u64 v[30:31], v[46:47], 0, v[4:5]
	v_lshlrev_b32_e32 v4, 13, v3
	s_waitcnt lgkmcnt(6)
	v_cvt_pk_bf16_f32 v12, v34, v32
	s_waitcnt lgkmcnt(4)
	v_cvt_pk_bf16_f32 v13, v36, v38
	s_waitcnt lgkmcnt(2)
	v_cvt_pk_bf16_f32 v14, v40, v42
	s_waitcnt lgkmcnt(0)
	v_cvt_pk_bf16_f32 v15, v44, v48
	global_store_dwordx4 v[30:31], v[12:15], off
	v_lshl_add_u64 v[16:17], v[46:47], 0, v[4:5]
	s_nop 0
	v_cvt_pk_bf16_f32 v12, v35, v33
	v_cvt_pk_bf16_f32 v13, v37, v39
	v_cvt_pk_bf16_f32 v14, v41, v43
	v_cvt_pk_bf16_f32 v15, v45, v49
	global_store_dwordx4 v[16:17], v[12:15], off
	s_waitcnt lgkmcnt(0)

; __device__ __forceinline__ void transpose_item(const float* W, int K, int N, bf16_t* WT, LAS float* scr, int item, int lane, int perm_cols) {
;     const int nblk = N / 32, kb = item / nblk, nb = item % nblk, k0 = 64 * kb, n0 = 32 * nb;
; #pragma unroll 8
;     for (int i = 0; i < 32; ++i) { const int kk = 2 * i + (lane >> 5); scr[kk * 33 + (lane & 31)] = W[(size_t)(k0 + kk) * N + n0 + (lane & 31)]; }
.LBB0_48:
	v_mov_b32_e32 v173, v5
	s_lshl_b32 s44, s41, 1
	s_lshl_b32 s45, s42, 1
	v_or_b32_e32 v172, s45, v16
	s_add_i32 s46, s44, 4
	s_add_i32 s47, s45, 4
	v_mov_b32_e32 v127, v5
	s_add_i32 s51, s45, 8
	v_lshlrev_b64 v[140:141], 14, v[172:173]
	v_or_b32_e32 v126, s46, v3
	v_or_b32_e32 v172, s47, v16
	v_mov_b32_e32 v125, v5
	v_or_b32_e32 v124, s44, v3
	s_add_i32 s55, s45, 12
	v_lshlrev_b64 v[126:127], 14, v[126:127]
	v_lshlrev_b64 v[142:143], 14, v[172:173]
	v_or_b32_e32 v172, s51, v16
	s_add_i32 s50, s44, 8
	s_add_i32 s54, s44, 12
	s_add_i32 s57, s45, 16
	v_lshlrev_b64 v[124:125], 14, v[124:125]
	v_lshl_add_u64 v[140:141], v[14:15], 0, v[140:141]
	v_lshl_add_u64 v[126:127], v[14:15], 0, v[126:127]
	v_lshlrev_b64 v[144:145], 14, v[172:173]
	v_or_b32_e32 v172, s55, v16
	v_mov_b32_e32 v129, v5
	v_mov_b32_e32 v131, v5
	s_add_i32 s59, s45, 20
	v_or_b32_e32 v128, s50, v3
	v_or_b32_e32 v130, s54, v3
	v_lshl_add_u64 v[124:125], v[14:15], 0, v[124:125]
	v_lshl_add_u64 v[142:143], v[14:15], 0, v[142:143]
	global_load_dword v123, v[140:141], off
	global_load_dword v156, v[124:125], off
	global_load_dword v157, v[142:143], off
	global_load_dword v158, v[126:127], off
	v_lshlrev_b64 v[126:127], 14, v[172:173]
	v_or_b32_e32 v172, s57, v16
	s_add_i32 s56, s44, 16
	s_add_i32 s58, s44, 20
	s_add_i32 s65, s45, 24
	v_lshlrev_b64 v[128:129], 14, v[128:129]
	v_lshlrev_b64 v[130:131], 14, v[130:131]
	v_lshl_add_u64 v[124:125], v[14:15], 0, v[144:145]
	v_lshl_add_u64 v[126:127], v[14:15], 0, v[126:127]
	v_lshlrev_b64 v[140:141], 14, v[172:173]
	v_or_b32_e32 v172, s59, v16
	v_mov_b32_e32 v133, v5
	v_mov_b32_e32 v135, v5
	s_add_i32 s64, s44, 24
	s_add_i32 s66, s44, 28
	s_add_i32 s67, s45, 28
	v_or_b32_e32 v132, s56, v3
	v_or_b32_e32 v134, s58, v3
	v_lshl_add_u64 v[128:129], v[14:15], 0, v[128:129]
	v_lshl_add_u64 v[130:131], v[14:15], 0, v[130:131]
	global_load_dword v159, v[124:125], off
	global_load_dword v160, v[128:129], off
	global_load_dword v161, v[126:127], off
	global_load_dword v162, v[130:131], off
	v_lshlrev_b64 v[126:127], 14, v[172:173]
	v_or_b32_e32 v172, s65, v16
	v_mov_b32_e32 v137, v5
	v_mov_b32_e32 v139, v5
	v_or_b32_e32 v136, s64, v3
	v_or_b32_e32 v138, s66, v3
	v_lshlrev_b64 v[132:133], 14, v[132:133]
	v_lshlrev_b64 v[134:135], 14, v[134:135]
	v_lshl_add_u64 v[124:125], v[14:15], 0, v[140:141]
	v_lshl_add_u64 v[126:127], v[14:15], 0, v[126:127]
	v_lshlrev_b64 v[128:129], 14, v[172:173]
	v_or_b32_e32 v172, s67, v16
	v_lshlrev_b64 v[136:137], 14, v[136:137]
	v_lshlrev_b64 v[138:139], 14, v[138:139]
	v_lshl_add_u64 v[132:133], v[14:15], 0, v[132:133]
	v_lshl_add_u64 v[134:135], v[14:15], 0, v[134:135]
	global_load_dword v163, v[124:125], off
	global_load_dword v164, v[132:133], off
	global_load_dword v165, v[126:127], off
	global_load_dword v166, v[134:135], off
	v_lshl_add_u64 v[124:125], v[14:15], 0, v[128:129]
	v_lshlrev_b64 v[126:127], 14, v[172:173]
	v_lshl_add_u64 v[136:137], v[14:15], 0, v[136:137]
	v_lshl_add_u64 v[138:139], v[14:15], 0, v[138:139]
	v_lshl_add_u64 v[126:127], v[14:15], 0, v[126:127]
	global_load_dword v172, v[124:125], off
	global_load_dword v167, v[136:137], off
	global_load_dword v168, v[126:127], off
	global_load_dword v169, v[138:139], off
	v_or_b32_e32 v126, s44, v1
	v_or_b32_e32 v124, s45, v2
	s_add_i32 s42, s42, 16
	s_add_i32 s41, s41, 16
	s_add_i32 s43, s43, -16
	v_mad_u64_u32 v[124:125], s[44:45], v124, s3, v[6:7]
	v_mad_u64_u32 v[126:127], s[44:45], v126, s3, v[6:7]
	v_or_b32_e32 v125, s46, v1
	v_or_b32_e32 v127, s47, v2
	v_or_b32_e32 v134, s50, v1
	v_or_b32_e32 v132, s51, v2
	v_or_b32_e32 v138, s54, v1
	v_or_b32_e32 v136, s55, v2
	v_or_b32_e32 v142, s56, v1
	v_or_b32_e32 v140, s57, v2
	v_or_b32_e32 v146, s58, v1
	v_or_b32_e32 v144, s59, v2
	v_or_b32_e32 v150, s64, v1
	v_or_b32_e32 v148, s65, v2
	v_or_b32_e32 v154, s66, v1
	v_or_b32_e32 v152, s67, v2
	s_cmp_lg_u32 s43, 0
	v_mad_u64_u32 v[128:129], s[44:45], v127, s3, v[6:7]
	v_mad_u64_u32 v[130:131], s[44:45], v125, s3, v[6:7]
	v_mad_u64_u32 v[132:133], s[44:45], v132, s3, v[6:7]
	v_mad_u64_u32 v[134:135], s[44:45], v134, s3, v[6:7]
	v_mad_u64_u32 v[136:137], s[44:45], v136, s3, v[6:7]
	v_mad_u64_u32 v[138:139], s[44:45], v138, s3, v[6:7]
	v_mad_u64_u32 v[140:141], s[44:45], v140, s3, v[6:7]
	v_mad_u64_u32 v[142:143], s[44:45], v142, s3, v[6:7]
	v_mad_u64_u32 v[144:145], s[44:45], v144, s3, v[6:7]
	v_mad_u64_u32 v[146:147], s[44:45], v146, s3, v[6:7]
	v_mad_u64_u32 v[148:149], s[44:45], v148, s3, v[6:7]
	v_mad_u64_u32 v[150:151], s[44:45], v150, s3, v[6:7]
	v_mad_u64_u32 v[152:153], s[44:45], v152, s3, v[6:7]
	v_mad_u64_u32 v[154:155], s[44:45], v154, s3, v[6:7]
	s_lshl_b32 s44, s41, 1
	s_lshl_b32 s45, s42, 1
	v_or_b32_e32 v4, s45, v16
	s_add_i32 s46, s44, 4
	s_add_i32 s47, s45, 4
	v_mov_b32_e32 v33, v5
	s_add_i32 s51, s45, 8
	v_lshlrev_b64 v[46:47], 14, v[4:5]
	v_or_b32_e32 v32, s46, v3
	v_or_b32_e32 v4, s47, v16
	v_mov_b32_e32 v31, v5
	v_or_b32_e32 v30, s44, v3
	s_add_i32 s55, s45, 12
	v_lshlrev_b64 v[32:33], 14, v[32:33]
	v_lshlrev_b64 v[48:49], 14, v[4:5]
	v_or_b32_e32 v4, s51, v16
	s_add_i32 s50, s44, 8
	s_add_i32 s54, s44, 12
	s_add_i32 s57, s45, 16
	v_lshlrev_b64 v[30:31], 14, v[30:31]
	v_lshl_add_u64 v[46:47], v[14:15], 0, v[46:47]
	v_lshl_add_u64 v[32:33], v[14:15], 0, v[32:33]
	v_lshlrev_b64 v[50:51], 14, v[4:5]
	v_or_b32_e32 v4, s55, v16
	v_mov_b32_e32 v35, v5
	v_mov_b32_e32 v37, v5
	s_add_i32 s59, s45, 20
	v_or_b32_e32 v34, s50, v3
	v_or_b32_e32 v36, s54, v3
	v_lshl_add_u64 v[30:31], v[14:15], 0, v[30:31]
	v_lshl_add_u64 v[48:49], v[14:15], 0, v[48:49]
	global_load_dword v9, v[46:47], off
	global_load_dword v62, v[30:31], off
; __device__ __forceinline__ void transpose_item(const float* W, int K, int N, bf16_t* WT, LAS float* scr, int item, int lane, int perm_cols) {
;     const int nblk = N / 32, kb = item / nblk, nb = item % nblk, k0 = 64 * kb, n0 = 32 * nb;
; #pragma unroll 8
;     for (int i = 0; i < 32; ++i) { const int kk = 2 * i + (lane >> 5); scr[kk * 33 + (lane & 31)] = W[(size_t)(k0 + kk) * N + n0 + (lane & 31)]; }
	global_load_dword v63, v[48:49], off
	global_load_dword v64, v[32:33], off
	v_lshlrev_b64 v[32:33], 14, v[4:5]
	v_or_b32_e32 v4, s57, v16
	s_add_i32 s56, s44, 16
	s_add_i32 s58, s44, 20
	s_add_i32 s65, s45, 24
	v_lshlrev_b64 v[34:35], 14, v[34:35]
	v_lshlrev_b64 v[36:37], 14, v[36:37]
	v_lshl_add_u64 v[30:31], v[14:15], 0, v[50:51]
	v_lshl_add_u64 v[32:33], v[14:15], 0, v[32:33]
	v_lshlrev_b64 v[46:47], 14, v[4:5]
	v_or_b32_e32 v4, s59, v16
	v_mov_b32_e32 v39, v5
	v_mov_b32_e32 v41, v5
	s_add_i32 s64, s44, 24
	s_add_i32 s66, s44, 28
	s_add_i32 s67, s45, 28
	v_or_b32_e32 v38, s56, v3
	v_or_b32_e32 v40, s58, v3
	v_lshl_add_u64 v[34:35], v[14:15], 0, v[34:35]
	v_lshl_add_u64 v[36:37], v[14:15], 0, v[36:37]
	global_load_dword v65, v[30:31], off
	global_load_dword v66, v[34:35], off
	global_load_dword v67, v[32:33], off
	global_load_dword v68, v[36:37], off
	v_lshlrev_b64 v[32:33], 14, v[4:5]
	v_or_b32_e32 v4, s65, v16
	v_mov_b32_e32 v43, v5
	v_mov_b32_e32 v45, v5
	v_or_b32_e32 v42, s64, v3
	v_or_b32_e32 v44, s66, v3
	v_lshlrev_b64 v[38:39], 14, v[38:39]
	v_lshlrev_b64 v[40:41], 14, v[40:41]
	v_lshl_add_u64 v[30:31], v[14:15], 0, v[46:47]
	v_lshl_add_u64 v[32:33], v[14:15], 0, v[32:33]
	v_lshlrev_b64 v[34:35], 14, v[4:5]
	v_or_b32_e32 v4, s67, v16
	v_lshlrev_b64 v[42:43], 14, v[42:43]
	v_lshlrev_b64 v[44:45], 14, v[44:45]
	v_lshl_add_u64 v[38:39], v[14:15], 0, v[38:39]
	v_lshl_add_u64 v[40:41], v[14:15], 0, v[40:41]
	global_load_dword v69, v[30:31], off
	global_load_dword v70, v[38:39], off
	global_load_dword v71, v[32:33], off
	global_load_dword v72, v[40:41], off
	v_lshl_add_u64 v[30:31], v[14:15], 0, v[34:35]
	v_lshlrev_b64 v[32:33], 14, v[4:5]
	v_lshl_add_u64 v[42:43], v[14:15], 0, v[42:43]
	v_lshl_add_u64 v[44:45], v[14:15], 0, v[44:45]
	v_lshl_add_u64 v[32:33], v[14:15], 0, v[32:33]
	global_load_dword v4, v[30:31], off
	global_load_dword v73, v[42:43], off
	global_load_dword v74, v[32:33], off
	global_load_dword v75, v[44:45], off
	v_or_b32_e32 v32, s44, v1
	v_or_b32_e32 v30, s45, v2
	s_add_i32 s42, s42, 16
	s_add_i32 s41, s41, 16
	s_add_i32 s43, s43, -16
	v_mad_u64_u32 v[30:31], s[44:45], v30, s3, v[6:7]
	v_mad_u64_u32 v[32:33], s[44:45], v32, s3, v[6:7]
	v_or_b32_e32 v31, s46, v1
	v_or_b32_e32 v33, s47, v2
	v_or_b32_e32 v40, s50, v1
	v_or_b32_e32 v38, s51, v2
	v_or_b32_e32 v44, s54, v1
	v_or_b32_e32 v42, s55, v2
	v_or_b32_e32 v48, s56, v1
	v_or_b32_e32 v46, s57, v2
	v_or_b32_e32 v52, s58, v1
	v_or_b32_e32 v50, s59, v2
	v_or_b32_e32 v56, s64, v1
	v_or_b32_e32 v54, s65, v2
	v_or_b32_e32 v60, s66, v1
	v_or_b32_e32 v58, s67, v2
	s_cmp_lg_u32 s43, 0
	v_mad_u64_u32 v[34:35], s[44:45], v33, s3, v[6:7]
	v_mad_u64_u32 v[36:37], s[44:45], v31, s3, v[6:7]
	v_mad_u64_u32 v[38:39], s[44:45], v38, s3, v[6:7]
	v_mad_u64_u32 v[40:41], s[44:45], v40, s3, v[6:7]
	v_mad_u64_u32 v[42:43], s[44:45], v42, s3, v[6:7]
	v_mad_u64_u32 v[44:45], s[44:45], v44, s3, v[6:7]
	v_mad_u64_u32 v[46:47], s[44:45], v46, s3, v[6:7]
	v_mad_u64_u32 v[48:49], s[44:45], v48, s3, v[6:7]
	v_mad_u64_u32 v[50:51], s[44:45], v50, s3, v[6:7]
	v_mad_u64_u32 v[52:53], s[44:45], v52, s3, v[6:7]
	v_mad_u64_u32 v[54:55], s[44:45], v54, s3, v[6:7]
	v_mad_u64_u32 v[56:57], s[44:45], v56, s3, v[6:7]
	v_mad_u64_u32 v[58:59], s[44:45], v58, s3, v[6:7]
	v_mad_u64_u32 v[60:61], s[44:45], v60, s3, v[6:7]
	s_waitcnt vmcnt(31)
	ds_write_b32 v124, v123
	s_waitcnt vmcnt(30)
	ds_write_b32 v126, v156
	s_waitcnt vmcnt(29)
	ds_write_b32 v128, v157
	s_waitcnt vmcnt(28)
	ds_write_b32 v130, v158
	s_waitcnt vmcnt(27)
	ds_write_b32 v132, v159
	s_waitcnt vmcnt(26)
; #define LAS __attribute__((address_space(3)))
; __device__ __forceinline__ unsigned cvt_pk_bf16(float lo, float hi) { f32x2 v = {lo, hi}; bf16x2_t b = __builtin_convertvector(v, bf16x2_t); return __builtin_bit_cast(unsigned, b); }
; __device__ __forceinline__ void transpose_item(const float* W, int K, int N, bf16_t* WT, LAS float* scr, int item, int lane, int perm_cols) {
;     ...
;     for (int i = 0; i < 32; ++i) { const int kk = 2 * i + (lane >> 5); scr[kk * 33 + (lane & 31)] = W[(size_t)(k0 + kk) * N + n0 + (lane & 31)]; }
;     asm volatile("s_waitcnt lgkmcnt(0)" ::: "memory");
;     const int c = lane & 7; const bool perm = n0 < perm_cols;
; #pragma unroll
;     for (int j = 0; j < 4; ++j) { const int n = (lane >> 3) + 8 * j; const int sn = perm ? ((n >> 1) + 16 * (n & 1)) : n; const LAS float* s = scr + (8 * c) * 33 + sn;
;         u32x4 o; o.x = cvt_pk_bf16(s[0 * 33], s[1 * 33]); o.y = cvt_pk_bf16(s[2 * 33], s[3 * 33]); o.z = cvt_pk_bf16(s[4 * 33], s[5 * 33]); o.w = cvt_pk_bf16(s[6 * 33], s[7 * 33]);
;         *(u32x4*)(WT + (size_t)(n0 + n) * K + k0 + 8 * c) = o; }
;     asm volatile("s_waitcnt lgkmcnt(0)" ::: "memory");
	ds_write_b32 v134, v160
	s_waitcnt vmcnt(25)
	ds_write_b32 v136, v161
	s_waitcnt vmcnt(24)
	ds_write_b32 v138, v162
	s_waitcnt vmcnt(23)
	ds_write_b32 v140, v163
	s_waitcnt vmcnt(22)
	ds_write_b32 v142, v164
	s_waitcnt vmcnt(21)
	ds_write_b32 v144, v165
	s_waitcnt vmcnt(20)
	ds_write_b32 v146, v166
	s_waitcnt vmcnt(19)
	ds_write_b32 v148, v172
	s_waitcnt vmcnt(18)
	ds_write_b32 v150, v167
	s_waitcnt vmcnt(17)
	ds_write_b32 v152, v168
	s_waitcnt vmcnt(16)
	ds_write_b32 v154, v169
	s_waitcnt vmcnt(15)
	ds_write_b32 v30, v9
	s_waitcnt vmcnt(14)
	ds_write_b32 v32, v62
	s_waitcnt vmcnt(13)
	ds_write_b32 v34, v63
	s_waitcnt vmcnt(12)
	ds_write_b32 v36, v64
	s_waitcnt vmcnt(11)
	ds_write_b32 v38, v65
	s_waitcnt vmcnt(10)
	ds_write_b32 v40, v66
	s_waitcnt vmcnt(9)
	ds_write_b32 v42, v67
	s_waitcnt vmcnt(8)
	ds_write_b32 v44, v68
	s_waitcnt vmcnt(7)
	ds_write_b32 v46, v69
	s_waitcnt vmcnt(6)
	ds_write_b32 v48, v70
	s_waitcnt vmcnt(5)
	ds_write_b32 v50, v71
	s_waitcnt vmcnt(4)
	ds_write_b32 v52, v72
	s_waitcnt vmcnt(3)
	ds_write_b32 v54, v4
	s_waitcnt vmcnt(2)
	ds_write_b32 v56, v73
	s_waitcnt vmcnt(1)
	ds_write_b32 v58, v74
	s_waitcnt vmcnt(0)
	ds_write_b32 v60, v75
	s_waitcnt lgkmcnt(0)
	ds_read2_b32 v[30:31], v20 offset0:33 offset1:41
	ds_read2_b32 v[32:33], v20 offset1:8
	ds_read2_b32 v[34:35], v20 offset0:66 offset1:74
	ds_read2_b32 v[36:37], v20 offset0:99 offset1:107
	ds_read2_b32 v[38:39], v20 offset0:132 offset1:140
	ds_read2_b32 v[40:41], v20 offset0:165 offset1:173
	ds_read2_b32 v[42:43], v20 offset0:198 offset1:206
	ds_read2_b32 v[44:45], v20 offset0:231 offset1:239
	v_lshlrev_b64 v[12:13], 23, v[12:13]
	v_lshl_add_u64 v[12:13], s[6:7], 0, v[12:13]
	v_lshlrev_b32_e32 v4, 1, v11
	v_lshl_add_u64 v[12:13], v[12:13], 0, v[4:5]
	v_mov_b32_e32 v11, v5
	v_or_b32_e32 v3, v17, v18
	v_lshl_add_u64 v[46:47], v[12:13], 0, v[10:11]
	v_lshlrev_b32_e32 v4, 11, v3
	s_waitcnt lgkmcnt(6)
	v_cvt_pk_bf16_f32 v12, v32, v30
	s_waitcnt lgkmcnt(4)
	v_cvt_pk_bf16_f32 v13, v34, v36
	s_waitcnt lgkmcnt(2)
	v_cvt_pk_bf16_f32 v14, v38, v40
	s_waitcnt lgkmcnt(0)
	v_cvt_pk_bf16_f32 v15, v42, v44
	v_lshl_add_u64 v[48:49], v[46:47], 0, v[4:5]
	global_store_dwordx4 v[48:49], v[12:15], off
	v_or_b32_e32 v3, v17, v21
	v_lshlrev_b32_e32 v4, 11, v3
	v_cvt_pk_bf16_f32 v12, v33, v31
	v_cvt_pk_bf16_f32 v13, v35, v37
	v_cvt_pk_bf16_f32 v14, v39, v41
	v_cvt_pk_bf16_f32 v15, v43, v45
	ds_read2_b32 v[32:33], v20 offset0:49 offset1:57
	ds_read2_b32 v[34:35], v20 offset0:16 offset1:24
	ds_read2_b32 v[36:37], v20 offset0:82 offset1:90
	ds_read2_b32 v[38:39], v20 offset0:115 offset1:123
	ds_read2_b32 v[40:41], v20 offset0:148 offset1:156
	ds_read2_b32 v[42:43], v20 offset0:181 offset1:189
	ds_read2_b32 v[44:45], v20 offset0:214 offset1:222
	ds_read2_b32 v[48:49], v20 offset0:247 offset1:255
	v_or_b32_e32 v3, v17, v22
	v_lshl_add_u64 v[30:31], v[46:47], 0, v[4:5]
	v_lshlrev_b32_e32 v4, 11, v3
	v_or_b32_e32 v3, v17, v23
	global_store_dwordx4 v[30:31], v[12:15], off
	v_lshl_add_u64 v[30:31], v[46:47], 0, v[4:5]
	v_lshlrev_b32_e32 v4, 11, v3
	s_waitcnt lgkmcnt(6)
	v_cvt_pk_bf16_f32 v12, v34, v32
	s_waitcnt lgkmcnt(4)
	v_cvt_pk_bf16_f32 v13, v36, v38
	s_waitcnt lgkmcnt(2)
	v_cvt_pk_bf16_f32 v14, v40, v42
	s_waitcnt lgkmcnt(0)
	v_cvt_pk_bf16_f32 v15, v44, v48
	global_store_dwordx4 v[30:31], v[12:15], off
	v_lshl_add_u64 v[16:17], v[46:47], 0, v[4:5]
	s_nop 0
	v_cvt_pk_bf16_f32 v12, v35, v33
	v_cvt_pk_bf16_f32 v13, v37, v39
	v_cvt_pk_bf16_f32 v14, v41, v43
	v_cvt_pk_bf16_f32 v15, v45, v49
	global_store_dwordx4 v[16:17], v[12:15], off
	s_waitcnt lgkmcnt(0)

; __device__ __forceinline__ void transpose_item(const float* W, int K, int N, bf16_t* WT, LAS float* scr, int item, int lane, int perm_cols) {
;     const int nblk = N / 32, kb = item / nblk, nb = item % nblk, k0 = 64 * kb, n0 = 32 * nb;
; #pragma unroll 8
;     for (int i = 0; i < 32; ++i) { const int kk = 2 * i + (lane >> 5); scr[kk * 33 + (lane & 31)] = W[(size_t)(k0 + kk) * N + n0 + (lane & 31)]; }
.LBB0_53:
	v_mov_b32_e32 v173, v5
	s_lshl_b32 s42, s28, 1
	s_lshl_b32 s43, s29, 1
	v_or_b32_e32 v172, s43, v16
	s_add_i32 s44, s42, 4
	s_add_i32 s45, s43, 4
	v_mov_b32_e32 v127, v5
	s_add_i32 s47, s43, 8
	v_lshlrev_b64 v[140:141], 12, v[172:173]
	v_or_b32_e32 v126, s44, v3
	v_or_b32_e32 v172, s45, v16
	v_mov_b32_e32 v125, v5
	v_or_b32_e32 v124, s42, v3
	s_add_i32 s51, s43, 12
	v_lshlrev_b64 v[126:127], 12, v[126:127]
	v_lshlrev_b64 v[142:143], 12, v[172:173]
	v_or_b32_e32 v172, s47, v16
	s_add_i32 s46, s42, 8
	s_add_i32 s50, s42, 12
	s_add_i32 s55, s43, 16
	v_lshlrev_b64 v[124:125], 12, v[124:125]
	v_lshl_add_u64 v[140:141], v[14:15], 0, v[140:141]
	v_lshl_add_u64 v[126:127], v[14:15], 0, v[126:127]
	v_lshlrev_b64 v[144:145], 12, v[172:173]
	v_or_b32_e32 v172, s51, v16
	v_mov_b32_e32 v129, v5
	v_mov_b32_e32 v131, v5
	s_add_i32 s57, s43, 20
	v_or_b32_e32 v128, s46, v3
	v_or_b32_e32 v130, s50, v3
	v_lshl_add_u64 v[124:125], v[14:15], 0, v[124:125]
	v_lshl_add_u64 v[142:143], v[14:15], 0, v[142:143]
	global_load_dword v123, v[140:141], off
	global_load_dword v156, v[124:125], off
	global_load_dword v157, v[142:143], off
	global_load_dword v158, v[126:127], off
	v_lshlrev_b64 v[126:127], 12, v[172:173]
	v_or_b32_e32 v172, s55, v16
	s_add_i32 s54, s42, 16
	s_add_i32 s56, s42, 20
	s_add_i32 s59, s43, 24
	v_lshlrev_b64 v[128:129], 12, v[128:129]
	v_lshlrev_b64 v[130:131], 12, v[130:131]
	v_lshl_add_u64 v[124:125], v[14:15], 0, v[144:145]
	v_lshl_add_u64 v[126:127], v[14:15], 0, v[126:127]
	v_lshlrev_b64 v[140:141], 12, v[172:173]
	v_or_b32_e32 v172, s57, v16
	v_mov_b32_e32 v133, v5
	v_mov_b32_e32 v135, v5
	s_add_i32 s58, s42, 24
	s_add_i32 s64, s42, 28
	s_add_i32 s65, s43, 28
	v_or_b32_e32 v132, s54, v3
	v_or_b32_e32 v134, s56, v3
	v_lshl_add_u64 v[128:129], v[14:15], 0, v[128:129]
	v_lshl_add_u64 v[130:131], v[14:15], 0, v[130:131]
	global_load_dword v159, v[124:125], off
	global_load_dword v160, v[128:129], off
	global_load_dword v161, v[126:127], off
	global_load_dword v162, v[130:131], off
	v_lshlrev_b64 v[126:127], 12, v[172:173]
	v_or_b32_e32 v172, s59, v16
	v_mov_b32_e32 v137, v5
	v_mov_b32_e32 v139, v5
	v_or_b32_e32 v136, s58, v3
	v_or_b32_e32 v138, s64, v3
	v_lshlrev_b64 v[132:133], 12, v[132:133]
	v_lshlrev_b64 v[134:135], 12, v[134:135]
	v_lshl_add_u64 v[124:125], v[14:15], 0, v[140:141]
	v_lshl_add_u64 v[126:127], v[14:15], 0, v[126:127]
	v_lshlrev_b64 v[128:129], 12, v[172:173]
	v_or_b32_e32 v172, s65, v16
	v_lshlrev_b64 v[136:137], 12, v[136:137]
	v_lshlrev_b64 v[138:139], 12, v[138:139]
	v_lshl_add_u64 v[132:133], v[14:15], 0, v[132:133]
	v_lshl_add_u64 v[134:135], v[14:15], 0, v[134:135]
	global_load_dword v163, v[124:125], off
	global_load_dword v164, v[132:133], off
	global_load_dword v165, v[126:127], off
	global_load_dword v166, v[134:135], off
	v_lshl_add_u64 v[124:125], v[14:15], 0, v[128:129]
	v_lshlrev_b64 v[126:127], 12, v[172:173]
	v_lshl_add_u64 v[136:137], v[14:15], 0, v[136:137]
	v_lshl_add_u64 v[138:139], v[14:15], 0, v[138:139]
	v_lshl_add_u64 v[126:127], v[14:15], 0, v[126:127]
	global_load_dword v172, v[124:125], off
	global_load_dword v167, v[136:137], off
	global_load_dword v168, v[126:127], off
	global_load_dword v169, v[138:139], off
	v_or_b32_e32 v126, s42, v1
	v_or_b32_e32 v124, s43, v2
	s_add_i32 s29, s29, 16
	s_add_i32 s28, s28, 16
	s_add_i32 s41, s41, -16
	v_mad_u64_u32 v[124:125], s[42:43], v124, s3, v[6:7]
	v_mad_u64_u32 v[126:127], s[42:43], v126, s3, v[6:7]
	v_or_b32_e32 v125, s44, v1
	v_or_b32_e32 v127, s45, v2
	v_or_b32_e32 v134, s46, v1
	v_or_b32_e32 v132, s47, v2
	v_or_b32_e32 v138, s50, v1
	v_or_b32_e32 v136, s51, v2
	v_or_b32_e32 v142, s54, v1
	v_or_b32_e32 v140, s55, v2
	v_or_b32_e32 v146, s56, v1
	v_or_b32_e32 v144, s57, v2
	v_or_b32_e32 v150, s58, v1
	v_or_b32_e32 v148, s59, v2
	v_or_b32_e32 v154, s64, v1
	v_or_b32_e32 v152, s65, v2
	s_cmp_lg_u32 s41, 0
	v_mad_u64_u32 v[128:129], s[42:43], v127, s3, v[6:7]
	v_mad_u64_u32 v[130:131], s[42:43], v125, s3, v[6:7]
	v_mad_u64_u32 v[132:133], s[42:43], v132, s3, v[6:7]
	v_mad_u64_u32 v[134:135], s[42:43], v134, s3, v[6:7]
	v_mad_u64_u32 v[136:137], s[42:43], v136, s3, v[6:7]
	v_mad_u64_u32 v[138:139], s[42:43], v138, s3, v[6:7]
	v_mad_u64_u32 v[140:141], s[42:43], v140, s3, v[6:7]
	v_mad_u64_u32 v[142:143], s[42:43], v142, s3, v[6:7]
	v_mad_u64_u32 v[144:145], s[42:43], v144, s3, v[6:7]
	v_mad_u64_u32 v[146:147], s[42:43], v146, s3, v[6:7]
	v_mad_u64_u32 v[148:149], s[42:43], v148, s3, v[6:7]
	v_mad_u64_u32 v[150:151], s[42:43], v150, s3, v[6:7]
	v_mad_u64_u32 v[152:153], s[42:43], v152, s3, v[6:7]
	v_mad_u64_u32 v[154:155], s[42:43], v154, s3, v[6:7]
	s_lshl_b32 s42, s28, 1
	s_lshl_b32 s43, s29, 1
	v_or_b32_e32 v4, s43, v16
	s_add_i32 s44, s42, 4
	s_add_i32 s45, s43, 4
	v_mov_b32_e32 v33, v5
	s_add_i32 s47, s43, 8
	v_lshlrev_b64 v[46:47], 12, v[4:5]
	v_or_b32_e32 v32, s44, v3
	v_or_b32_e32 v4, s45, v16
	v_mov_b32_e32 v31, v5
	v_or_b32_e32 v30, s42, v3
	s_add_i32 s51, s43, 12
	v_lshlrev_b64 v[32:33], 12, v[32:33]
	v_lshlrev_b64 v[48:49], 12, v[4:5]
	v_or_b32_e32 v4, s47, v16
	s_add_i32 s46, s42, 8
	s_add_i32 s50, s42, 12
	s_add_i32 s55, s43, 16
	v_lshlrev_b64 v[30:31], 12, v[30:31]
	v_lshl_add_u64 v[46:47], v[14:15], 0, v[46:47]
	v_lshl_add_u64 v[32:33], v[14:15], 0, v[32:33]
	v_lshlrev_b64 v[50:51], 12, v[4:5]
	v_or_b32_e32 v4, s51, v16
	v_mov_b32_e32 v35, v5
	v_mov_b32_e32 v37, v5
	s_add_i32 s57, s43, 20
	v_or_b32_e32 v34, s46, v3
	v_or_b32_e32 v36, s50, v3
	v_lshl_add_u64 v[30:31], v[14:15], 0, v[30:31]
	v_lshl_add_u64 v[48:49], v[14:15], 0, v[48:49]
	global_load_dword v9, v[46:47], off
	global_load_dword v62, v[30:31], off
; __device__ __forceinline__ void transpose_item(const float* W, int K, int N, bf16_t* WT, LAS float* scr, int item, int lane, int perm_cols) {
;     ...
;     for (int i = 0; i < 32; ++i) { const int kk = 2 * i + (lane >> 5); scr[kk * 33 + (lane & 31)] = W[(size_t)(k0 + kk) * N + n0 + (lane & 31)]; }
	global_load_dword v63, v[48:49], off
	global_load_dword v64, v[32:33], off
	v_lshlrev_b64 v[32:33], 12, v[4:5]
	v_or_b32_e32 v4, s55, v16
	s_add_i32 s54, s42, 16
	s_add_i32 s56, s42, 20
	s_add_i32 s59, s43, 24
	v_lshlrev_b64 v[34:35], 12, v[34:35]
	v_lshlrev_b64 v[36:37], 12, v[36:37]
	v_lshl_add_u64 v[30:31], v[14:15], 0, v[50:51]
	v_lshl_add_u64 v[32:33], v[14:15], 0, v[32:33]
	v_lshlrev_b64 v[46:47], 12, v[4:5]
	v_or_b32_e32 v4, s57, v16
	v_mov_b32_e32 v39, v5
	v_mov_b32_e32 v41, v5
	s_add_i32 s58, s42, 24
	s_add_i32 s64, s42, 28
	s_add_i32 s65, s43, 28
	v_or_b32_e32 v38, s54, v3
	v_or_b32_e32 v40, s56, v3
	v_lshl_add_u64 v[34:35], v[14:15], 0, v[34:35]
	v_lshl_add_u64 v[36:37], v[14:15], 0, v[36:37]
	global_load_dword v65, v[30:31], off
	global_load_dword v66, v[34:35], off
	global_load_dword v67, v[32:33], off
	global_load_dword v68, v[36:37], off
	v_lshlrev_b64 v[32:33], 12, v[4:5]
	v_or_b32_e32 v4, s59, v16
	v_mov_b32_e32 v43, v5
	v_mov_b32_e32 v45, v5
	v_or_b32_e32 v42, s58, v3
	v_or_b32_e32 v44, s64, v3
	v_lshlrev_b64 v[38:39], 12, v[38:39]
	v_lshlrev_b64 v[40:41], 12, v[40:41]
	v_lshl_add_u64 v[30:31], v[14:15], 0, v[46:47]
	v_lshl_add_u64 v[32:33], v[14:15], 0, v[32:33]
	v_lshlrev_b64 v[34:35], 12, v[4:5]
	v_or_b32_e32 v4, s65, v16
	v_lshlrev_b64 v[42:43], 12, v[42:43]
	v_lshlrev_b64 v[44:45], 12, v[44:45]
	v_lshl_add_u64 v[38:39], v[14:15], 0, v[38:39]
	v_lshl_add_u64 v[40:41], v[14:15], 0, v[40:41]
	global_load_dword v69, v[30:31], off
	global_load_dword v70, v[38:39], off
	global_load_dword v71, v[32:33], off
	global_load_dword v72, v[40:41], off
	v_lshl_add_u64 v[30:31], v[14:15], 0, v[34:35]
	v_lshlrev_b64 v[32:33], 12, v[4:5]
	v_lshl_add_u64 v[42:43], v[14:15], 0, v[42:43]
	v_lshl_add_u64 v[44:45], v[14:15], 0, v[44:45]
	v_lshl_add_u64 v[32:33], v[14:15], 0, v[32:33]
	global_load_dword v4, v[30:31], off
	global_load_dword v73, v[42:43], off
	global_load_dword v74, v[32:33], off
	global_load_dword v75, v[44:45], off
	v_or_b32_e32 v32, s42, v1
	v_or_b32_e32 v30, s43, v2
	s_add_i32 s29, s29, 16
	s_add_i32 s28, s28, 16
	s_add_i32 s41, s41, -16
	v_mad_u64_u32 v[30:31], s[42:43], v30, s3, v[6:7]
	v_mad_u64_u32 v[32:33], s[42:43], v32, s3, v[6:7]
	v_or_b32_e32 v31, s44, v1
	v_or_b32_e32 v33, s45, v2
	v_or_b32_e32 v40, s46, v1
	v_or_b32_e32 v38, s47, v2
	v_or_b32_e32 v44, s50, v1
	v_or_b32_e32 v42, s51, v2
	v_or_b32_e32 v48, s54, v1
	v_or_b32_e32 v46, s55, v2
	v_or_b32_e32 v52, s56, v1
	v_or_b32_e32 v50, s57, v2
	v_or_b32_e32 v56, s58, v1
	v_or_b32_e32 v54, s59, v2
	v_or_b32_e32 v60, s64, v1
	v_or_b32_e32 v58, s65, v2
	s_cmp_lg_u32 s41, 0
	v_mad_u64_u32 v[34:35], s[42:43], v33, s3, v[6:7]
	v_mad_u64_u32 v[36:37], s[42:43], v31, s3, v[6:7]
	v_mad_u64_u32 v[38:39], s[42:43], v38, s3, v[6:7]
	v_mad_u64_u32 v[40:41], s[42:43], v40, s3, v[6:7]
	v_mad_u64_u32 v[42:43], s[42:43], v42, s3, v[6:7]
	v_mad_u64_u32 v[44:45], s[42:43], v44, s3, v[6:7]
	v_mad_u64_u32 v[46:47], s[42:43], v46, s3, v[6:7]
	v_mad_u64_u32 v[48:49], s[42:43], v48, s3, v[6:7]
	v_mad_u64_u32 v[50:51], s[42:43], v50, s3, v[6:7]
	v_mad_u64_u32 v[52:53], s[42:43], v52, s3, v[6:7]
	v_mad_u64_u32 v[54:55], s[42:43], v54, s3, v[6:7]
	v_mad_u64_u32 v[56:57], s[42:43], v56, s3, v[6:7]
	v_mad_u64_u32 v[58:59], s[42:43], v58, s3, v[6:7]
	v_mad_u64_u32 v[60:61], s[42:43], v60, s3, v[6:7]
	s_waitcnt vmcnt(31)
	ds_write_b32 v124, v123
	s_waitcnt vmcnt(30)
	ds_write_b32 v126, v156
	s_waitcnt vmcnt(29)
	ds_write_b32 v128, v157
	s_waitcnt vmcnt(28)
	ds_write_b32 v130, v158
	s_waitcnt vmcnt(27)
	ds_write_b32 v132, v159
	s_waitcnt vmcnt(26)
; #define LAS __attribute__((address_space(3)))
; __device__ __forceinline__ unsigned cvt_pk_bf16(float lo, float hi) { f32x2 v = {lo, hi}; bf16x2_t b = __builtin_convertvector(v, bf16x2_t); return __builtin_bit_cast(unsigned, b); }
; __device__ __forceinline__ void transpose_item(const float* W, int K, int N, bf16_t* WT, LAS float* scr, int item, int lane, int perm_cols) {
;     ...
;     for (int i = 0; i < 32; ++i) { const int kk = 2 * i + (lane >> 5); scr[kk * 33 + (lane & 31)] = W[(size_t)(k0 + kk) * N + n0 + (lane & 31)]; }
;     asm volatile("s_waitcnt lgkmcnt(0)" ::: "memory");
;     const int c = lane & 7; const bool perm = n0 < perm_cols;
; #pragma unroll
;     for (int j = 0; j < 4; ++j) { const int n = (lane >> 3) + 8 * j; const int sn = perm ? ((n >> 1) + 16 * (n & 1)) : n; const LAS float* s = scr + (8 * c) * 33 + sn;
;         u32x4 o; o.x = cvt_pk_bf16(s[0 * 33], s[1 * 33]); o.y = cvt_pk_bf16(s[2 * 33], s[3 * 33]); o.z = cvt_pk_bf16(s[4 * 33], s[5 * 33]); o.w = cvt_pk_bf16(s[6 * 33], s[7 * 33]);
;         *(u32x4*)(WT + (size_t)(n0 + n) * K + k0 + 8 * c) = o; }
	ds_write_b32 v134, v160
	s_waitcnt vmcnt(25)
	ds_write_b32 v136, v161
	s_waitcnt vmcnt(24)
	ds_write_b32 v138, v162
	s_waitcnt vmcnt(23)
	ds_write_b32 v140, v163
	s_waitcnt vmcnt(22)
	ds_write_b32 v142, v164
	s_waitcnt vmcnt(21)
	ds_write_b32 v144, v165
	s_waitcnt vmcnt(20)
	ds_write_b32 v146, v166
	s_waitcnt vmcnt(19)
	ds_write_b32 v148, v172
	s_waitcnt vmcnt(18)
	ds_write_b32 v150, v167
	s_waitcnt vmcnt(17)
	ds_write_b32 v152, v168
	s_waitcnt vmcnt(16)
	ds_write_b32 v154, v169
	s_waitcnt vmcnt(15)
	ds_write_b32 v30, v9
	s_waitcnt vmcnt(14)
	ds_write_b32 v32, v62
	s_waitcnt vmcnt(13)
	ds_write_b32 v34, v63
	s_waitcnt vmcnt(12)
	ds_write_b32 v36, v64
	s_waitcnt vmcnt(11)
	ds_write_b32 v38, v65
	s_waitcnt vmcnt(10)
	ds_write_b32 v40, v66
	s_waitcnt vmcnt(9)
	ds_write_b32 v42, v67
	s_waitcnt vmcnt(8)
	ds_write_b32 v44, v68
	s_waitcnt vmcnt(7)
	ds_write_b32 v46, v69
	s_waitcnt vmcnt(6)
	ds_write_b32 v48, v70
	s_waitcnt vmcnt(5)
	ds_write_b32 v50, v71
	s_waitcnt vmcnt(4)
	ds_write_b32 v52, v72
	s_waitcnt vmcnt(3)
	ds_write_b32 v54, v4
	s_waitcnt vmcnt(2)
	ds_write_b32 v56, v73
	s_waitcnt vmcnt(1)
	ds_write_b32 v58, v74
	s_waitcnt vmcnt(0)
	ds_write_b32 v60, v75
	s_waitcnt lgkmcnt(0)
	ds_read2_b32 v[30:31], v20 offset0:33 offset1:41
	ds_read2_b32 v[32:33], v20 offset1:8
	ds_read2_b32 v[34:35], v20 offset0:66 offset1:74
	ds_read2_b32 v[36:37], v20 offset0:99 offset1:107
	ds_read2_b32 v[38:39], v20 offset0:132 offset1:140
	ds_read2_b32 v[40:41], v20 offset0:165 offset1:173
	ds_read2_b32 v[42:43], v20 offset0:198 offset1:206
	ds_read2_b32 v[44:45], v20 offset0:231 offset1:239
	v_lshlrev_b64 v[12:13], 22, v[12:13]
	v_lshl_add_u64 v[12:13], s[8:9], 0, v[12:13]
	v_lshlrev_b32_e32 v4, 1, v11
	v_lshl_add_u64 v[12:13], v[12:13], 0, v[4:5]
	v_mov_b32_e32 v11, v5
	v_or_b32_e32 v3, v17, v18
	v_lshl_add_u64 v[46:47], v[12:13], 0, v[10:11]
	v_lshlrev_b32_e32 v4, 12, v3
	s_waitcnt lgkmcnt(6)
	v_cvt_pk_bf16_f32 v12, v32, v30
	s_waitcnt lgkmcnt(4)
	v_cvt_pk_bf16_f32 v13, v34, v36
	s_waitcnt lgkmcnt(2)
	v_cvt_pk_bf16_f32 v14, v38, v40
	s_waitcnt lgkmcnt(0)
	v_cvt_pk_bf16_f32 v15, v42, v44
	v_lshl_add_u64 v[48:49], v[46:47], 0, v[4:5]
	global_store_dwordx4 v[48:49], v[12:15], off
	v_or_b32_e32 v3, v17, v21
	v_lshlrev_b32_e32 v4, 12, v3
	v_cvt_pk_bf16_f32 v12, v33, v31
	v_cvt_pk_bf16_f32 v13, v35, v37
	v_cvt_pk_bf16_f32 v14, v39, v41
	v_cvt_pk_bf16_f32 v15, v43, v45
	ds_read2_b32 v[32:33], v20 offset0:49 offset1:57
	ds_read2_b32 v[34:35], v20 offset0:16 offset1:24
	ds_read2_b32 v[36:37], v20 offset0:82 offset1:90
	ds_read2_b32 v[38:39], v20 offset0:115 offset1:123
	ds_read2_b32 v[40:41], v20 offset0:148 offset1:156
	ds_read2_b32 v[42:43], v20 offset0:181 offset1:189
	ds_read2_b32 v[44:45], v20 offset0:214 offset1:222
	ds_read2_b32 v[48:49], v20 offset0:247 offset1:255
	v_or_b32_e32 v3, v17, v22
	v_lshl_add_u64 v[30:31], v[46:47], 0, v[4:5]
	v_lshlrev_b32_e32 v4, 12, v3
	v_or_b32_e32 v3, v17, v23
	global_store_dwordx4 v[30:31], v[12:15], off
	v_lshl_add_u64 v[30:31], v[46:47], 0, v[4:5]
	v_lshlrev_b32_e32 v4, 12, v3
	s_waitcnt lgkmcnt(6)
	v_cvt_pk_bf16_f32 v12, v34, v32
	s_waitcnt lgkmcnt(4)
	v_cvt_pk_bf16_f32 v13, v36, v38
	s_waitcnt lgkmcnt(2)
	v_cvt_pk_bf16_f32 v14, v40, v42
	s_waitcnt lgkmcnt(0)
	v_cvt_pk_bf16_f32 v15, v44, v48
	global_store_dwordx4 v[30:31], v[12:15], off
	v_lshl_add_u64 v[16:17], v[46:47], 0, v[4:5]
	s_nop 0
	v_cvt_pk_bf16_f32 v12, v35, v33
	v_cvt_pk_bf16_f32 v13, v37, v39
	v_cvt_pk_bf16_f32 v14, v41, v43
	v_cvt_pk_bf16_f32 v15, v45, v49
	global_store_dwordx4 v[16:17], v[12:15], off
	s_waitcnt lgkmcnt(0)

; __device__ __forceinline__ void transpose_item(const float* W, int K, int N, bf16_t* WT, LAS float* scr, int item, int lane, int perm_cols) {
;     ...
;     for (int i = 0; i < 32; ++i) { const int kk = 2 * i + (lane >> 5); scr[kk * 33 + (lane & 31)] = W[(size_t)(k0 + kk) * N + n0 + (lane & 31)]; }
.LBB0_58:
	v_mov_b32_e32 v173, v5
	s_lshl_b32 s29, s26, 1
	s_lshl_b32 s41, s27, 1
	v_or_b32_e32 v172, s41, v16
	s_add_i32 s44, s29, 4
	s_add_i32 s45, s41, 4
	v_mov_b32_e32 v127, v5
	s_add_i32 s47, s41, 8
	v_lshlrev_b64 v[140:141], 14, v[172:173]
	v_or_b32_e32 v126, s44, v3
	v_or_b32_e32 v172, s45, v16
	v_mov_b32_e32 v125, v5
	v_or_b32_e32 v124, s29, v3
	s_add_i32 s51, s41, 12
	v_lshlrev_b64 v[126:127], 14, v[126:127]
	v_lshlrev_b64 v[142:143], 14, v[172:173]
	v_or_b32_e32 v172, s47, v16
	s_add_i32 s46, s29, 8
	s_add_i32 s50, s29, 12
	s_add_i32 s55, s41, 16
	v_lshlrev_b64 v[124:125], 14, v[124:125]
	v_lshl_add_u64 v[140:141], v[14:15], 0, v[140:141]
	v_lshl_add_u64 v[126:127], v[14:15], 0, v[126:127]
	v_lshlrev_b64 v[144:145], 14, v[172:173]
	v_or_b32_e32 v172, s51, v16
	v_mov_b32_e32 v129, v5
	v_mov_b32_e32 v131, v5
	s_add_i32 s57, s41, 20
	v_or_b32_e32 v128, s46, v3
	v_or_b32_e32 v130, s50, v3
	v_lshl_add_u64 v[124:125], v[14:15], 0, v[124:125]
	v_lshl_add_u64 v[142:143], v[14:15], 0, v[142:143]
	global_load_dword v123, v[140:141], off
	global_load_dword v156, v[124:125], off
	global_load_dword v157, v[142:143], off
	global_load_dword v158, v[126:127], off
	v_lshlrev_b64 v[126:127], 14, v[172:173]
	v_or_b32_e32 v172, s55, v16
	s_add_i32 s54, s29, 16
	s_add_i32 s56, s29, 20
	s_add_i32 s59, s41, 24
	v_lshlrev_b64 v[128:129], 14, v[128:129]
	v_lshlrev_b64 v[130:131], 14, v[130:131]
	v_lshl_add_u64 v[124:125], v[14:15], 0, v[144:145]
	v_lshl_add_u64 v[126:127], v[14:15], 0, v[126:127]
	v_lshlrev_b64 v[140:141], 14, v[172:173]
	v_or_b32_e32 v172, s57, v16
	v_mov_b32_e32 v133, v5
	v_mov_b32_e32 v135, v5
	s_add_i32 s58, s29, 24
	s_add_i32 s64, s29, 28
	s_add_i32 s65, s41, 28
	v_or_b32_e32 v132, s54, v3
	v_or_b32_e32 v134, s56, v3
	v_lshl_add_u64 v[128:129], v[14:15], 0, v[128:129]
	v_lshl_add_u64 v[130:131], v[14:15], 0, v[130:131]
	global_load_dword v159, v[124:125], off
	global_load_dword v160, v[128:129], off
	global_load_dword v161, v[126:127], off
	global_load_dword v162, v[130:131], off
	v_lshlrev_b64 v[126:127], 14, v[172:173]
	v_or_b32_e32 v172, s59, v16
	v_mov_b32_e32 v137, v5
	v_mov_b32_e32 v139, v5
	v_or_b32_e32 v136, s58, v3
	v_or_b32_e32 v138, s64, v3
	v_lshlrev_b64 v[132:133], 14, v[132:133]
	v_lshlrev_b64 v[134:135], 14, v[134:135]
	v_lshl_add_u64 v[124:125], v[14:15], 0, v[140:141]
	v_lshl_add_u64 v[126:127], v[14:15], 0, v[126:127]
	v_lshlrev_b64 v[128:129], 14, v[172:173]
	v_or_b32_e32 v172, s65, v16
	v_lshlrev_b64 v[136:137], 14, v[136:137]
	v_lshlrev_b64 v[138:139], 14, v[138:139]
	v_lshl_add_u64 v[132:133], v[14:15], 0, v[132:133]
	v_lshl_add_u64 v[134:135], v[14:15], 0, v[134:135]
	global_load_dword v163, v[124:125], off
	global_load_dword v164, v[132:133], off
	global_load_dword v165, v[126:127], off
	global_load_dword v166, v[134:135], off
	v_lshl_add_u64 v[124:125], v[14:15], 0, v[128:129]
	v_lshlrev_b64 v[126:127], 14, v[172:173]
	v_lshl_add_u64 v[136:137], v[14:15], 0, v[136:137]
	v_lshl_add_u64 v[138:139], v[14:15], 0, v[138:139]
	v_lshl_add_u64 v[126:127], v[14:15], 0, v[126:127]
	global_load_dword v172, v[124:125], off
	global_load_dword v167, v[136:137], off
	global_load_dword v168, v[126:127], off
	global_load_dword v169, v[138:139], off
	v_or_b32_e32 v126, s29, v1
	v_or_b32_e32 v124, s41, v2
	s_add_i32 s27, s27, 16
	s_add_i32 s26, s26, 16
	s_add_i32 s28, s28, -16
	v_mad_u64_u32 v[124:125], s[42:43], v124, s3, v[6:7]
	v_mad_u64_u32 v[126:127], s[42:43], v126, s3, v[6:7]
	v_or_b32_e32 v125, s44, v1
	v_or_b32_e32 v127, s45, v2
	v_or_b32_e32 v134, s46, v1
	v_or_b32_e32 v132, s47, v2
	v_or_b32_e32 v138, s50, v1
	v_or_b32_e32 v136, s51, v2
	v_or_b32_e32 v142, s54, v1
	v_or_b32_e32 v140, s55, v2
	v_or_b32_e32 v146, s56, v1
	v_or_b32_e32 v144, s57, v2
	v_or_b32_e32 v150, s58, v1
	v_or_b32_e32 v148, s59, v2
	v_or_b32_e32 v154, s64, v1
	v_or_b32_e32 v152, s65, v2
	s_cmp_lg_u32 s28, 0
	v_mad_u64_u32 v[128:129], s[42:43], v127, s3, v[6:7]
	v_mad_u64_u32 v[130:131], s[42:43], v125, s3, v[6:7]
	v_mad_u64_u32 v[132:133], s[42:43], v132, s3, v[6:7]
	v_mad_u64_u32 v[134:135], s[42:43], v134, s3, v[6:7]
	v_mad_u64_u32 v[136:137], s[42:43], v136, s3, v[6:7]
	v_mad_u64_u32 v[138:139], s[42:43], v138, s3, v[6:7]
	v_mad_u64_u32 v[140:141], s[42:43], v140, s3, v[6:7]
	v_mad_u64_u32 v[142:143], s[42:43], v142, s3, v[6:7]
	v_mad_u64_u32 v[144:145], s[42:43], v144, s3, v[6:7]
	v_mad_u64_u32 v[146:147], s[42:43], v146, s3, v[6:7]
	v_mad_u64_u32 v[148:149], s[42:43], v148, s3, v[6:7]
	v_mad_u64_u32 v[150:151], s[42:43], v150, s3, v[6:7]
	v_mad_u64_u32 v[152:153], s[42:43], v152, s3, v[6:7]
	v_mad_u64_u32 v[154:155], s[42:43], v154, s3, v[6:7]
	s_lshl_b32 s29, s26, 1
	s_lshl_b32 s41, s27, 1
	v_or_b32_e32 v4, s41, v16
	s_add_i32 s44, s29, 4
	s_add_i32 s45, s41, 4
	v_mov_b32_e32 v33, v5
	s_add_i32 s47, s41, 8
	v_lshlrev_b64 v[46:47], 14, v[4:5]
	v_or_b32_e32 v32, s44, v3
	v_or_b32_e32 v4, s45, v16
	v_mov_b32_e32 v31, v5
	v_or_b32_e32 v30, s29, v3
	s_add_i32 s51, s41, 12
	v_lshlrev_b64 v[32:33], 14, v[32:33]
	v_lshlrev_b64 v[48:49], 14, v[4:5]
	v_or_b32_e32 v4, s47, v16
	s_add_i32 s46, s29, 8
	s_add_i32 s50, s29, 12
	s_add_i32 s55, s41, 16
	v_lshlrev_b64 v[30:31], 14, v[30:31]
	v_lshl_add_u64 v[46:47], v[14:15], 0, v[46:47]
	v_lshl_add_u64 v[32:33], v[14:15], 0, v[32:33]
	v_lshlrev_b64 v[50:51], 14, v[4:5]
	v_or_b32_e32 v4, s51, v16
	v_mov_b32_e32 v35, v5
	v_mov_b32_e32 v37, v5
	s_add_i32 s57, s41, 20
	v_or_b32_e32 v34, s46, v3
	v_or_b32_e32 v36, s50, v3
	v_lshl_add_u64 v[30:31], v[14:15], 0, v[30:31]
	v_lshl_add_u64 v[48:49], v[14:15], 0, v[48:49]
	global_load_dword v9, v[46:47], off
	global_load_dword v62, v[30:31], off
; __device__ __forceinline__ void transpose_item(const float* W, int K, int N, bf16_t* WT, LAS float* scr, int item, int lane, int perm_cols) {
;     ...
;     for (int i = 0; i < 32; ++i) { const int kk = 2 * i + (lane >> 5); scr[kk * 33 + (lane & 31)] = W[(size_t)(k0 + kk) * N + n0 + (lane & 31)]; }
	global_load_dword v63, v[48:49], off
	global_load_dword v64, v[32:33], off
	v_lshlrev_b64 v[32:33], 14, v[4:5]
	v_or_b32_e32 v4, s55, v16
	s_add_i32 s54, s29, 16
	s_add_i32 s56, s29, 20
	s_add_i32 s59, s41, 24
	v_lshlrev_b64 v[34:35], 14, v[34:35]
	v_lshlrev_b64 v[36:37], 14, v[36:37]
	v_lshl_add_u64 v[30:31], v[14:15], 0, v[50:51]
	v_lshl_add_u64 v[32:33], v[14:15], 0, v[32:33]
	v_lshlrev_b64 v[46:47], 14, v[4:5]
	v_or_b32_e32 v4, s57, v16
	v_mov_b32_e32 v39, v5
	v_mov_b32_e32 v41, v5
	s_add_i32 s58, s29, 24
	s_add_i32 s64, s29, 28
	s_add_i32 s65, s41, 28
	v_or_b32_e32 v38, s54, v3
	v_or_b32_e32 v40, s56, v3
	v_lshl_add_u64 v[34:35], v[14:15], 0, v[34:35]
	v_lshl_add_u64 v[36:37], v[14:15], 0, v[36:37]
	global_load_dword v65, v[30:31], off
	global_load_dword v66, v[34:35], off
	global_load_dword v67, v[32:33], off
	global_load_dword v68, v[36:37], off
	v_lshlrev_b64 v[32:33], 14, v[4:5]
	v_or_b32_e32 v4, s59, v16
	v_mov_b32_e32 v43, v5
	v_mov_b32_e32 v45, v5
	v_or_b32_e32 v42, s58, v3
	v_or_b32_e32 v44, s64, v3
	v_lshlrev_b64 v[38:39], 14, v[38:39]
	v_lshlrev_b64 v[40:41], 14, v[40:41]
	v_lshl_add_u64 v[30:31], v[14:15], 0, v[46:47]
	v_lshl_add_u64 v[32:33], v[14:15], 0, v[32:33]
	v_lshlrev_b64 v[34:35], 14, v[4:5]
	v_or_b32_e32 v4, s65, v16
	v_lshlrev_b64 v[42:43], 14, v[42:43]
	v_lshlrev_b64 v[44:45], 14, v[44:45]
	v_lshl_add_u64 v[38:39], v[14:15], 0, v[38:39]
	v_lshl_add_u64 v[40:41], v[14:15], 0, v[40:41]
	global_load_dword v69, v[30:31], off
	global_load_dword v70, v[38:39], off
	global_load_dword v71, v[32:33], off
	global_load_dword v72, v[40:41], off
	v_lshl_add_u64 v[30:31], v[14:15], 0, v[34:35]
	v_lshlrev_b64 v[32:33], 14, v[4:5]
	v_lshl_add_u64 v[42:43], v[14:15], 0, v[42:43]
	v_lshl_add_u64 v[44:45], v[14:15], 0, v[44:45]
	v_lshl_add_u64 v[32:33], v[14:15], 0, v[32:33]
	global_load_dword v4, v[30:31], off
	global_load_dword v73, v[42:43], off
	global_load_dword v74, v[32:33], off
	global_load_dword v75, v[44:45], off
	v_or_b32_e32 v32, s29, v1
	v_or_b32_e32 v30, s41, v2
	s_add_i32 s27, s27, 16
	s_add_i32 s26, s26, 16
	s_add_i32 s28, s28, -16
	v_mad_u64_u32 v[30:31], s[42:43], v30, s3, v[6:7]
	v_mad_u64_u32 v[32:33], s[42:43], v32, s3, v[6:7]
	v_or_b32_e32 v31, s44, v1
	v_or_b32_e32 v33, s45, v2
	v_or_b32_e32 v40, s46, v1
	v_or_b32_e32 v38, s47, v2
	v_or_b32_e32 v44, s50, v1
	v_or_b32_e32 v42, s51, v2
	v_or_b32_e32 v48, s54, v1
	v_or_b32_e32 v46, s55, v2
	v_or_b32_e32 v52, s56, v1
	v_or_b32_e32 v50, s57, v2
	v_or_b32_e32 v56, s58, v1
	v_or_b32_e32 v54, s59, v2
	v_or_b32_e32 v60, s64, v1
	v_or_b32_e32 v58, s65, v2
	s_cmp_lg_u32 s28, 0
	v_mad_u64_u32 v[34:35], s[42:43], v33, s3, v[6:7]
	v_mad_u64_u32 v[36:37], s[42:43], v31, s3, v[6:7]
	v_mad_u64_u32 v[38:39], s[42:43], v38, s3, v[6:7]
	v_mad_u64_u32 v[40:41], s[42:43], v40, s3, v[6:7]
	v_mad_u64_u32 v[42:43], s[42:43], v42, s3, v[6:7]
	v_mad_u64_u32 v[44:45], s[42:43], v44, s3, v[6:7]
	v_mad_u64_u32 v[46:47], s[42:43], v46, s3, v[6:7]
	v_mad_u64_u32 v[48:49], s[42:43], v48, s3, v[6:7]
	v_mad_u64_u32 v[50:51], s[42:43], v50, s3, v[6:7]
	v_mad_u64_u32 v[52:53], s[42:43], v52, s3, v[6:7]
	v_mad_u64_u32 v[54:55], s[42:43], v54, s3, v[6:7]
	v_mad_u64_u32 v[56:57], s[42:43], v56, s3, v[6:7]
	v_mad_u64_u32 v[58:59], s[42:43], v58, s3, v[6:7]
	v_mad_u64_u32 v[60:61], s[42:43], v60, s3, v[6:7]
	s_waitcnt vmcnt(31)
	ds_write_b32 v124, v123
	s_waitcnt vmcnt(30)
	ds_write_b32 v126, v156
	s_waitcnt vmcnt(29)
	ds_write_b32 v128, v157
	s_waitcnt vmcnt(28)
	ds_write_b32 v130, v158
	s_waitcnt vmcnt(27)
	ds_write_b32 v132, v159
	s_waitcnt vmcnt(26)
	ds_write_b32 v134, v160
	s_waitcnt vmcnt(25)
	ds_write_b32 v136, v161
	s_waitcnt vmcnt(24)
	ds_write_b32 v138, v162
	s_waitcnt vmcnt(23)
; #define LAS __attribute__((address_space(3)))
; __device__ __forceinline__ unsigned cvt_pk_bf16(float lo, float hi) { f32x2 v = {lo, hi}; bf16x2_t b = __builtin_convertvector(v, bf16x2_t); return __builtin_bit_cast(unsigned, b); }
; __device__ __forceinline__ void transpose_item(const float* W, int K, int N, bf16_t* WT, LAS float* scr, int item, int lane, int perm_cols) {
;     ...
;     for (int i = 0; i < 32; ++i) { const int kk = 2 * i + (lane >> 5); scr[kk * 33 + (lane & 31)] = W[(size_t)(k0 + kk) * N + n0 + (lane & 31)]; }
;     asm volatile("s_waitcnt lgkmcnt(0)" ::: "memory");
;     const int c = lane & 7; const bool perm = n0 < perm_cols;
; #pragma unroll
;     for (int j = 0; j < 4; ++j) { const int n = (lane >> 3) + 8 * j; const int sn = perm ? ((n >> 1) + 16 * (n & 1)) : n; const LAS float* s = scr + (8 * c) * 33 + sn;
;         u32x4 o; o.x = cvt_pk_bf16(s[0 * 33], s[1 * 33]); o.y = cvt_pk_bf16(s[2 * 33], s[3 * 33]); o.z = cvt_pk_bf16(s[4 * 33], s[5 * 33]); o.w = cvt_pk_bf16(s[6 * 33], s[7 * 33]);
;         *(u32x4*)(WT + (size_t)(n0 + n) * K + k0 + 8 * c) = o; }
	ds_write_b32 v140, v163
	s_waitcnt vmcnt(22)
	ds_write_b32 v142, v164
	s_waitcnt vmcnt(21)
	ds_write_b32 v144, v165
	s_waitcnt vmcnt(20)
	ds_write_b32 v146, v166
	s_waitcnt vmcnt(19)
	ds_write_b32 v148, v172
	s_waitcnt vmcnt(18)
	ds_write_b32 v150, v167
	s_waitcnt vmcnt(17)
	ds_write_b32 v152, v168
	s_waitcnt vmcnt(16)
	ds_write_b32 v154, v169
	s_waitcnt vmcnt(15)
	ds_write_b32 v30, v9
	s_waitcnt vmcnt(14)
	ds_write_b32 v32, v62
	s_waitcnt vmcnt(13)
	ds_write_b32 v34, v63
	s_waitcnt vmcnt(12)
	ds_write_b32 v36, v64
	s_waitcnt vmcnt(11)
	ds_write_b32 v38, v65
	s_waitcnt vmcnt(10)
	ds_write_b32 v40, v66
	s_waitcnt vmcnt(9)
	ds_write_b32 v42, v67
	s_waitcnt vmcnt(8)
	ds_write_b32 v44, v68
	s_waitcnt vmcnt(7)
	ds_write_b32 v46, v69
	s_waitcnt vmcnt(6)
	ds_write_b32 v48, v70
	s_waitcnt vmcnt(5)
	ds_write_b32 v50, v71
	s_waitcnt vmcnt(4)
	ds_write_b32 v52, v72
	s_waitcnt vmcnt(3)
	ds_write_b32 v54, v4
	s_waitcnt vmcnt(2)
	ds_write_b32 v56, v73
	s_waitcnt vmcnt(1)
	ds_write_b32 v58, v74
	s_waitcnt vmcnt(0)
	ds_write_b32 v60, v75
	s_waitcnt lgkmcnt(0)
	ds_read2_b32 v[30:31], v20 offset0:33 offset1:41
	ds_read2_b32 v[32:33], v20 offset1:8
	ds_read2_b32 v[34:35], v20 offset0:66 offset1:74
	ds_read2_b32 v[36:37], v20 offset0:99 offset1:107
	ds_read2_b32 v[38:39], v20 offset0:132 offset1:140
	ds_read2_b32 v[40:41], v20 offset0:165 offset1:173
	ds_read2_b32 v[42:43], v20 offset0:198 offset1:206
	ds_read2_b32 v[44:45], v20 offset0:231 offset1:239
	v_lshlrev_b64 v[12:13], 23, v[12:13]
	v_lshl_add_u64 v[12:13], s[12:13], 0, v[12:13]
	v_lshlrev_b32_e32 v4, 1, v11
	v_lshl_add_u64 v[12:13], v[12:13], 0, v[4:5]
	v_mov_b32_e32 v11, v5
	v_or_b32_e32 v3, v17, v18
	v_lshl_add_u64 v[46:47], v[12:13], 0, v[10:11]
	v_lshlrev_b32_e32 v4, 11, v3
	s_waitcnt lgkmcnt(6)
	v_cvt_pk_bf16_f32 v12, v32, v30
	s_waitcnt lgkmcnt(4)
	v_cvt_pk_bf16_f32 v13, v34, v36
	s_waitcnt lgkmcnt(2)
	v_cvt_pk_bf16_f32 v14, v38, v40
	s_waitcnt lgkmcnt(0)
	v_cvt_pk_bf16_f32 v15, v42, v44
	v_lshl_add_u64 v[48:49], v[46:47], 0, v[4:5]
	global_store_dwordx4 v[48:49], v[12:15], off
	v_or_b32_e32 v3, v17, v21
	v_lshlrev_b32_e32 v4, 11, v3
	v_cvt_pk_bf16_f32 v12, v33, v31
	v_cvt_pk_bf16_f32 v13, v35, v37
	v_cvt_pk_bf16_f32 v14, v39, v41
	v_cvt_pk_bf16_f32 v15, v43, v45
	ds_read2_b32 v[32:33], v20 offset0:49 offset1:57
	ds_read2_b32 v[34:35], v20 offset0:16 offset1:24
	ds_read2_b32 v[36:37], v20 offset0:82 offset1:90
	ds_read2_b32 v[38:39], v20 offset0:115 offset1:123
	ds_read2_b32 v[40:41], v20 offset0:148 offset1:156
	ds_read2_b32 v[42:43], v20 offset0:181 offset1:189
	ds_read2_b32 v[44:45], v20 offset0:214 offset1:222
	ds_read2_b32 v[48:49], v20 offset0:247 offset1:255
	v_or_b32_e32 v3, v17, v22
	v_lshl_add_u64 v[30:31], v[46:47], 0, v[4:5]
	v_lshlrev_b32_e32 v4, 11, v3
	v_or_b32_e32 v3, v17, v23
	global_store_dwordx4 v[30:31], v[12:15], off
	v_lshl_add_u64 v[30:31], v[46:47], 0, v[4:5]
	v_lshlrev_b32_e32 v4, 11, v3
	s_waitcnt lgkmcnt(6)
	v_cvt_pk_bf16_f32 v12, v34, v32
	s_waitcnt lgkmcnt(4)
	v_cvt_pk_bf16_f32 v13, v36, v38
	s_waitcnt lgkmcnt(2)
	v_cvt_pk_bf16_f32 v14, v40, v42
	s_waitcnt lgkmcnt(0)
	v_cvt_pk_bf16_f32 v15, v44, v48
	global_store_dwordx4 v[30:31], v[12:15], off
	v_lshl_add_u64 v[16:17], v[46:47], 0, v[4:5]
	v_readlane_b32 s68, v254, 16
	v_cvt_pk_bf16_f32 v12, v35, v33
	v_cvt_pk_bf16_f32 v13, v37, v39
	v_cvt_pk_bf16_f32 v14, v41, v43
	v_cvt_pk_bf16_f32 v15, v45, v49
	global_store_dwordx4 v[16:17], v[12:15], off
	s_waitcnt lgkmcnt(0)
	v_readlane_b32 s70, v254, 18
	v_readlane_b32 s71, v254, 19
	v_readlane_b32 s73, v254, 21
	v_readlane_b32 s69, v254, 17
	v_readlane_b32 s72, v254, 20
	v_readlane_b32 s74, v254, 22
	v_readlane_b32 s75, v254, 23

; __device__ __forceinline__ void transpose_item(const float* W, int K, int N, bf16_t* WT, LAS float* scr, int item, int lane, int perm_cols) {
;     ...
;     for (int i = 0; i < 32; ++i) { const int kk = 2 * i + (lane >> 5); scr[kk * 33 + (lane & 31)] = W[(size_t)(k0 + kk) * N + n0 + (lane & 31)]; }
.LBB0_63:
	v_mov_b32_e32 v173, v5
	s_lshl_b32 s27, s24, 1
	s_lshl_b32 s28, s25, 1
	v_or_b32_e32 v172, s28, v16
	s_add_i32 s41, s27, 4
	s_add_i32 s42, s28, 4
	v_mov_b32_e32 v127, v5
	s_add_i32 s44, s28, 8
	v_lshlrev_b64 v[140:141], 12, v[172:173]
	v_or_b32_e32 v126, s41, v3
	v_or_b32_e32 v172, s42, v16
	v_mov_b32_e32 v125, v5
	v_or_b32_e32 v124, s27, v3
	s_add_i32 s46, s28, 12
	v_lshlrev_b64 v[126:127], 12, v[126:127]
	v_lshlrev_b64 v[142:143], 12, v[172:173]
	v_or_b32_e32 v172, s44, v16
	s_add_i32 s43, s27, 8
	s_add_i32 s45, s27, 12
	s_add_i32 s50, s28, 16
	v_lshlrev_b64 v[124:125], 12, v[124:125]
	v_lshl_add_u64 v[140:141], v[14:15], 0, v[140:141]
	v_lshl_add_u64 v[126:127], v[14:15], 0, v[126:127]
	v_lshlrev_b64 v[144:145], 12, v[172:173]
	v_or_b32_e32 v172, s46, v16
	v_mov_b32_e32 v129, v5
	v_mov_b32_e32 v131, v5
	s_add_i32 s54, s28, 20
	v_or_b32_e32 v128, s43, v3
	v_or_b32_e32 v130, s45, v3
	v_lshl_add_u64 v[124:125], v[14:15], 0, v[124:125]
	v_lshl_add_u64 v[142:143], v[14:15], 0, v[142:143]
	global_load_dword v123, v[140:141], off
	global_load_dword v156, v[124:125], off
	global_load_dword v157, v[142:143], off
	global_load_dword v158, v[126:127], off
	v_lshlrev_b64 v[126:127], 12, v[172:173]
	v_or_b32_e32 v172, s50, v16
	s_add_i32 s47, s27, 16
	s_add_i32 s51, s27, 20
	s_add_i32 s56, s28, 24
	v_lshlrev_b64 v[128:129], 12, v[128:129]
	v_lshlrev_b64 v[130:131], 12, v[130:131]
	v_lshl_add_u64 v[124:125], v[14:15], 0, v[144:145]
	v_lshl_add_u64 v[126:127], v[14:15], 0, v[126:127]
	v_lshlrev_b64 v[140:141], 12, v[172:173]
	v_or_b32_e32 v172, s54, v16
	v_mov_b32_e32 v133, v5
	v_mov_b32_e32 v135, v5
	s_add_i32 s55, s27, 24
	s_add_i32 s57, s27, 28
	s_add_i32 s58, s28, 28
	v_or_b32_e32 v132, s47, v3
	v_or_b32_e32 v134, s51, v3
	v_lshl_add_u64 v[128:129], v[14:15], 0, v[128:129]
	v_lshl_add_u64 v[130:131], v[14:15], 0, v[130:131]
	global_load_dword v159, v[124:125], off
	global_load_dword v160, v[128:129], off
	global_load_dword v161, v[126:127], off
	global_load_dword v162, v[130:131], off
	v_lshlrev_b64 v[126:127], 12, v[172:173]
	v_or_b32_e32 v172, s56, v16
	v_mov_b32_e32 v137, v5
	v_mov_b32_e32 v139, v5
	v_or_b32_e32 v136, s55, v3
	v_or_b32_e32 v138, s57, v3
	v_lshlrev_b64 v[132:133], 12, v[132:133]
	v_lshlrev_b64 v[134:135], 12, v[134:135]
	v_lshl_add_u64 v[124:125], v[14:15], 0, v[140:141]
	v_lshl_add_u64 v[126:127], v[14:15], 0, v[126:127]
	v_lshlrev_b64 v[128:129], 12, v[172:173]
	v_or_b32_e32 v172, s58, v16
	v_lshlrev_b64 v[136:137], 12, v[136:137]
	v_lshlrev_b64 v[138:139], 12, v[138:139]
	v_lshl_add_u64 v[132:133], v[14:15], 0, v[132:133]
	v_lshl_add_u64 v[134:135], v[14:15], 0, v[134:135]
	global_load_dword v163, v[124:125], off
	global_load_dword v164, v[132:133], off
	global_load_dword v165, v[126:127], off
	global_load_dword v166, v[134:135], off
	v_lshl_add_u64 v[124:125], v[14:15], 0, v[128:129]
	v_lshlrev_b64 v[126:127], 12, v[172:173]
	v_lshl_add_u64 v[136:137], v[14:15], 0, v[136:137]
	v_lshl_add_u64 v[138:139], v[14:15], 0, v[138:139]
	v_lshl_add_u64 v[126:127], v[14:15], 0, v[126:127]
	global_load_dword v172, v[124:125], off
	global_load_dword v167, v[136:137], off
	global_load_dword v168, v[126:127], off
	global_load_dword v169, v[138:139], off
	v_or_b32_e32 v126, s27, v1
	v_or_b32_e32 v124, s28, v2
	s_add_i32 s25, s25, 16
	s_add_i32 s24, s24, 16
	s_add_i32 s26, s26, -16
	v_mad_u64_u32 v[124:125], s[28:29], v124, s3, v[6:7]
	v_mad_u64_u32 v[126:127], s[28:29], v126, s3, v[6:7]
	v_or_b32_e32 v125, s41, v1
	v_or_b32_e32 v127, s42, v2
	v_or_b32_e32 v134, s43, v1
	v_or_b32_e32 v132, s44, v2
	v_or_b32_e32 v138, s45, v1
	v_or_b32_e32 v136, s46, v2
	v_or_b32_e32 v142, s47, v1
	v_or_b32_e32 v140, s50, v2
	v_or_b32_e32 v146, s51, v1
	v_or_b32_e32 v144, s54, v2
	v_or_b32_e32 v150, s55, v1
	v_or_b32_e32 v148, s56, v2
	v_or_b32_e32 v154, s57, v1
	v_or_b32_e32 v152, s58, v2
	s_cmp_lg_u32 s26, 0
	v_mad_u64_u32 v[128:129], s[28:29], v127, s3, v[6:7]
	v_mad_u64_u32 v[130:131], s[28:29], v125, s3, v[6:7]
	v_mad_u64_u32 v[132:133], s[28:29], v132, s3, v[6:7]
	v_mad_u64_u32 v[134:135], s[28:29], v134, s3, v[6:7]
	v_mad_u64_u32 v[136:137], s[28:29], v136, s3, v[6:7]
	v_mad_u64_u32 v[138:139], s[28:29], v138, s3, v[6:7]
	v_mad_u64_u32 v[140:141], s[28:29], v140, s3, v[6:7]
	v_mad_u64_u32 v[142:143], s[28:29], v142, s3, v[6:7]
	v_mad_u64_u32 v[144:145], s[28:29], v144, s3, v[6:7]
	v_mad_u64_u32 v[146:147], s[28:29], v146, s3, v[6:7]
	v_mad_u64_u32 v[148:149], s[28:29], v148, s3, v[6:7]
	v_mad_u64_u32 v[150:151], s[28:29], v150, s3, v[6:7]
	v_mad_u64_u32 v[152:153], s[28:29], v152, s3, v[6:7]
	v_mad_u64_u32 v[154:155], s[28:29], v154, s3, v[6:7]
	s_lshl_b32 s27, s24, 1
	s_lshl_b32 s28, s25, 1
	v_or_b32_e32 v4, s28, v16
	s_add_i32 s41, s27, 4
	s_add_i32 s42, s28, 4
	v_mov_b32_e32 v33, v5
	s_add_i32 s44, s28, 8
	v_lshlrev_b64 v[46:47], 12, v[4:5]
	v_or_b32_e32 v32, s41, v3
	v_or_b32_e32 v4, s42, v16
	v_mov_b32_e32 v31, v5
	v_or_b32_e32 v30, s27, v3
	s_add_i32 s46, s28, 12
	v_lshlrev_b64 v[32:33], 12, v[32:33]
	v_lshlrev_b64 v[48:49], 12, v[4:5]
	v_or_b32_e32 v4, s44, v16
	s_add_i32 s43, s27, 8
	s_add_i32 s45, s27, 12
	s_add_i32 s50, s28, 16
	v_lshlrev_b64 v[30:31], 12, v[30:31]
	v_lshl_add_u64 v[46:47], v[14:15], 0, v[46:47]
	v_lshl_add_u64 v[32:33], v[14:15], 0, v[32:33]
	v_lshlrev_b64 v[50:51], 12, v[4:5]
	v_or_b32_e32 v4, s46, v16
	v_mov_b32_e32 v35, v5
	v_mov_b32_e32 v37, v5
	s_add_i32 s54, s28, 20
	v_or_b32_e32 v34, s43, v3
	v_or_b32_e32 v36, s45, v3
	v_lshl_add_u64 v[30:31], v[14:15], 0, v[30:31]
	v_lshl_add_u64 v[48:49], v[14:15], 0, v[48:49]
	global_load_dword v9, v[46:47], off
	global_load_dword v62, v[30:31], off
; __device__ __forceinline__ void transpose_item(const float* W, int K, int N, bf16_t* WT, LAS float* scr, int item, int lane, int perm_cols) {
;     ...
;     for (int i = 0; i < 32; ++i) { const int kk = 2 * i + (lane >> 5); scr[kk * 33 + (lane & 31)] = W[(size_t)(k0 + kk) * N + n0 + (lane & 31)]; }
	global_load_dword v63, v[48:49], off
	global_load_dword v64, v[32:33], off
	v_lshlrev_b64 v[32:33], 12, v[4:5]
	v_or_b32_e32 v4, s50, v16
	s_add_i32 s47, s27, 16
	s_add_i32 s51, s27, 20
	s_add_i32 s56, s28, 24
	v_lshlrev_b64 v[34:35], 12, v[34:35]
	v_lshlrev_b64 v[36:37], 12, v[36:37]
	v_lshl_add_u64 v[30:31], v[14:15], 0, v[50:51]
	v_lshl_add_u64 v[32:33], v[14:15], 0, v[32:33]
	v_lshlrev_b64 v[46:47], 12, v[4:5]
	v_or_b32_e32 v4, s54, v16
	v_mov_b32_e32 v39, v5
	v_mov_b32_e32 v41, v5
	s_add_i32 s55, s27, 24
	s_add_i32 s57, s27, 28
	s_add_i32 s58, s28, 28
	v_or_b32_e32 v38, s47, v3
	v_or_b32_e32 v40, s51, v3
	v_lshl_add_u64 v[34:35], v[14:15], 0, v[34:35]
	v_lshl_add_u64 v[36:37], v[14:15], 0, v[36:37]
	global_load_dword v65, v[30:31], off
	global_load_dword v66, v[34:35], off
	global_load_dword v67, v[32:33], off
	global_load_dword v68, v[36:37], off
	v_lshlrev_b64 v[32:33], 12, v[4:5]
	v_or_b32_e32 v4, s56, v16
	v_mov_b32_e32 v43, v5
	v_mov_b32_e32 v45, v5
	v_or_b32_e32 v42, s55, v3
	v_or_b32_e32 v44, s57, v3
	v_lshlrev_b64 v[38:39], 12, v[38:39]
	v_lshlrev_b64 v[40:41], 12, v[40:41]
	v_lshl_add_u64 v[30:31], v[14:15], 0, v[46:47]
	v_lshl_add_u64 v[32:33], v[14:15], 0, v[32:33]
	v_lshlrev_b64 v[34:35], 12, v[4:5]
	v_or_b32_e32 v4, s58, v16
	v_lshlrev_b64 v[42:43], 12, v[42:43]
	v_lshlrev_b64 v[44:45], 12, v[44:45]
	v_lshl_add_u64 v[38:39], v[14:15], 0, v[38:39]
	v_lshl_add_u64 v[40:41], v[14:15], 0, v[40:41]
	global_load_dword v69, v[30:31], off
	global_load_dword v70, v[38:39], off
	global_load_dword v71, v[32:33], off
	global_load_dword v72, v[40:41], off
	v_lshl_add_u64 v[30:31], v[14:15], 0, v[34:35]
	v_lshlrev_b64 v[32:33], 12, v[4:5]
	v_lshl_add_u64 v[42:43], v[14:15], 0, v[42:43]
	v_lshl_add_u64 v[44:45], v[14:15], 0, v[44:45]
	v_lshl_add_u64 v[32:33], v[14:15], 0, v[32:33]
	global_load_dword v4, v[30:31], off
	global_load_dword v73, v[42:43], off
	global_load_dword v74, v[32:33], off
	global_load_dword v75, v[44:45], off
	v_or_b32_e32 v32, s27, v1
	v_or_b32_e32 v30, s28, v2
	s_add_i32 s25, s25, 16
	s_add_i32 s24, s24, 16
	s_add_i32 s26, s26, -16
	v_mad_u64_u32 v[30:31], s[28:29], v30, s3, v[6:7]
	v_mad_u64_u32 v[32:33], s[28:29], v32, s3, v[6:7]
	v_or_b32_e32 v31, s41, v1
	v_or_b32_e32 v33, s42, v2
	v_or_b32_e32 v40, s43, v1
	v_or_b32_e32 v38, s44, v2
	v_or_b32_e32 v44, s45, v1
	v_or_b32_e32 v42, s46, v2
	v_or_b32_e32 v48, s47, v1
	v_or_b32_e32 v46, s50, v2
	v_or_b32_e32 v52, s51, v1
	v_or_b32_e32 v50, s54, v2
	v_or_b32_e32 v56, s55, v1
	v_or_b32_e32 v54, s56, v2
	v_or_b32_e32 v60, s57, v1
	v_or_b32_e32 v58, s58, v2
	s_cmp_lg_u32 s26, 0
	v_mad_u64_u32 v[34:35], s[28:29], v33, s3, v[6:7]
	v_mad_u64_u32 v[36:37], s[28:29], v31, s3, v[6:7]
	v_mad_u64_u32 v[38:39], s[28:29], v38, s3, v[6:7]
	v_mad_u64_u32 v[40:41], s[28:29], v40, s3, v[6:7]
	v_mad_u64_u32 v[42:43], s[28:29], v42, s3, v[6:7]
	v_mad_u64_u32 v[44:45], s[28:29], v44, s3, v[6:7]
	v_mad_u64_u32 v[46:47], s[28:29], v46, s3, v[6:7]
	v_mad_u64_u32 v[48:49], s[28:29], v48, s3, v[6:7]
	v_mad_u64_u32 v[50:51], s[28:29], v50, s3, v[6:7]
	v_mad_u64_u32 v[52:53], s[28:29], v52, s3, v[6:7]
	v_mad_u64_u32 v[54:55], s[28:29], v54, s3, v[6:7]
	v_mad_u64_u32 v[56:57], s[28:29], v56, s3, v[6:7]
	v_mad_u64_u32 v[58:59], s[28:29], v58, s3, v[6:7]
	v_mad_u64_u32 v[60:61], s[28:29], v60, s3, v[6:7]
	s_waitcnt vmcnt(31)
	ds_write_b32 v124, v123
	s_waitcnt vmcnt(30)
	ds_write_b32 v126, v156
	s_waitcnt vmcnt(29)
	ds_write_b32 v128, v157
	s_waitcnt vmcnt(28)
	ds_write_b32 v130, v158
	s_waitcnt vmcnt(27)
	ds_write_b32 v132, v159
	s_waitcnt vmcnt(26)
	ds_write_b32 v134, v160
	s_waitcnt vmcnt(25)
	ds_write_b32 v136, v161
	s_waitcnt vmcnt(24)
; #define LAS __attribute__((address_space(3)))
; __device__ __forceinline__ unsigned cvt_pk_bf16(float lo, float hi) { f32x2 v = {lo, hi}; bf16x2_t b = __builtin_convertvector(v, bf16x2_t); return __builtin_bit_cast(unsigned, b); }
; __device__ __forceinline__ void transpose_item(const float* W, int K, int N, bf16_t* WT, LAS float* scr, int item, int lane, int perm_cols) {
;     ...
;     for (int i = 0; i < 32; ++i) { const int kk = 2 * i + (lane >> 5); scr[kk * 33 + (lane & 31)] = W[(size_t)(k0 + kk) * N + n0 + (lane & 31)]; }
;     asm volatile("s_waitcnt lgkmcnt(0)" ::: "memory");
;     const int c = lane & 7; const bool perm = n0 < perm_cols;
; #pragma unroll
;     for (int j = 0; j < 4; ++j) { const int n = (lane >> 3) + 8 * j; const int sn = perm ? ((n >> 1) + 16 * (n & 1)) : n; const LAS float* s = scr + (8 * c) * 33 + sn;
;         u32x4 o; o.x = cvt_pk_bf16(s[0 * 33], s[1 * 33]); o.y = cvt_pk_bf16(s[2 * 33], s[3 * 33]); o.z = cvt_pk_bf16(s[4 * 33], s[5 * 33]); o.w = cvt_pk_bf16(s[6 * 33], s[7 * 33]);
;         *(u32x4*)(WT + (size_t)(n0 + n) * K + k0 + 8 * c) = o; }
	ds_write_b32 v138, v162
	s_waitcnt vmcnt(23)
	ds_write_b32 v140, v163
	s_waitcnt vmcnt(22)
	ds_write_b32 v142, v164
	s_waitcnt vmcnt(21)
	ds_write_b32 v144, v165
	s_waitcnt vmcnt(20)
	ds_write_b32 v146, v166
	s_waitcnt vmcnt(19)
	ds_write_b32 v148, v172
	s_waitcnt vmcnt(18)
	ds_write_b32 v150, v167
	s_waitcnt vmcnt(17)
	ds_write_b32 v152, v168
	s_waitcnt vmcnt(16)
	ds_write_b32 v154, v169
	s_waitcnt vmcnt(15)
	ds_write_b32 v30, v9
	s_waitcnt vmcnt(14)
	ds_write_b32 v32, v62
	s_waitcnt vmcnt(13)
	ds_write_b32 v34, v63
	s_waitcnt vmcnt(12)
	ds_write_b32 v36, v64
	s_waitcnt vmcnt(11)
	ds_write_b32 v38, v65
	s_waitcnt vmcnt(10)
	ds_write_b32 v40, v66
	s_waitcnt vmcnt(9)
	ds_write_b32 v42, v67
	s_waitcnt vmcnt(8)
	ds_write_b32 v44, v68
	s_waitcnt vmcnt(7)
	ds_write_b32 v46, v69
	s_waitcnt vmcnt(6)
	ds_write_b32 v48, v70
	s_waitcnt vmcnt(5)
	ds_write_b32 v50, v71
	s_waitcnt vmcnt(4)
	ds_write_b32 v52, v72
	s_waitcnt vmcnt(3)
	ds_write_b32 v54, v4
	s_waitcnt vmcnt(2)
	ds_write_b32 v56, v73
	s_waitcnt vmcnt(1)
	ds_write_b32 v58, v74
	s_waitcnt vmcnt(0)
	ds_write_b32 v60, v75
	s_waitcnt lgkmcnt(0)
	ds_read2_b32 v[30:31], v20 offset0:33 offset1:41
	ds_read2_b32 v[32:33], v20 offset1:8
	ds_read2_b32 v[34:35], v20 offset0:66 offset1:74
	ds_read2_b32 v[36:37], v20 offset0:99 offset1:107
	ds_read2_b32 v[38:39], v20 offset0:132 offset1:140
	ds_read2_b32 v[40:41], v20 offset0:165 offset1:173
	ds_read2_b32 v[42:43], v20 offset0:198 offset1:206
	ds_read2_b32 v[44:45], v20 offset0:231 offset1:239
	v_lshl_add_u64 v[12:13], v[12:13], 1, s[14:15]
	v_lshlrev_b32_e32 v4, 1, v11
	v_lshl_add_u64 v[12:13], v[12:13], 0, v[4:5]
	v_mov_b32_e32 v11, v5
	v_or_b32_e32 v3, v17, v18
	v_lshl_add_u64 v[46:47], v[12:13], 0, v[10:11]
	v_lshlrev_b32_e32 v4, 11, v3
	s_waitcnt lgkmcnt(6)
	v_cvt_pk_bf16_f32 v12, v32, v30
	s_waitcnt lgkmcnt(4)
	v_cvt_pk_bf16_f32 v13, v34, v36
	s_waitcnt lgkmcnt(2)
	v_cvt_pk_bf16_f32 v14, v38, v40
	s_waitcnt lgkmcnt(0)
	v_cvt_pk_bf16_f32 v15, v42, v44
	v_lshl_add_u64 v[48:49], v[46:47], 0, v[4:5]
	global_store_dwordx4 v[48:49], v[12:15], off
	v_or_b32_e32 v3, v17, v21
	v_lshlrev_b32_e32 v4, 11, v3
	v_cvt_pk_bf16_f32 v12, v33, v31
	v_cvt_pk_bf16_f32 v13, v35, v37
	v_cvt_pk_bf16_f32 v14, v39, v41
	v_cvt_pk_bf16_f32 v15, v43, v45
	ds_read2_b32 v[32:33], v20 offset0:49 offset1:57
	ds_read2_b32 v[34:35], v20 offset0:16 offset1:24
	ds_read2_b32 v[36:37], v20 offset0:82 offset1:90
	ds_read2_b32 v[38:39], v20 offset0:115 offset1:123
	ds_read2_b32 v[40:41], v20 offset0:148 offset1:156
	ds_read2_b32 v[42:43], v20 offset0:181 offset1:189
	ds_read2_b32 v[44:45], v20 offset0:214 offset1:222
	ds_read2_b32 v[48:49], v20 offset0:247 offset1:255
	v_or_b32_e32 v3, v17, v22
	v_lshl_add_u64 v[30:31], v[46:47], 0, v[4:5]
	v_lshlrev_b32_e32 v4, 11, v3
	v_or_b32_e32 v3, v17, v23
	global_store_dwordx4 v[30:31], v[12:15], off
	v_lshl_add_u64 v[30:31], v[46:47], 0, v[4:5]
	v_lshlrev_b32_e32 v4, 11, v3
	s_waitcnt lgkmcnt(6)
	v_cvt_pk_bf16_f32 v12, v34, v32
	s_waitcnt lgkmcnt(4)
	v_cvt_pk_bf16_f32 v13, v36, v38
	s_waitcnt lgkmcnt(2)
	v_cvt_pk_bf16_f32 v14, v40, v42
	s_waitcnt lgkmcnt(0)
	v_cvt_pk_bf16_f32 v15, v44, v48
	global_store_dwordx4 v[30:31], v[12:15], off
	v_lshl_add_u64 v[16:17], v[46:47], 0, v[4:5]
	v_readlane_b32 s68, v254, 16
	v_cvt_pk_bf16_f32 v12, v35, v33
	v_cvt_pk_bf16_f32 v13, v37, v39
	v_cvt_pk_bf16_f32 v14, v41, v43
	v_cvt_pk_bf16_f32 v15, v45, v49
	global_store_dwordx4 v[16:17], v[12:15], off
	s_waitcnt lgkmcnt(0)
	v_readlane_b32 s70, v254, 18
	v_readlane_b32 s71, v254, 19
	v_readlane_b32 s73, v254, 21
	v_readlane_b32 s69, v254, 17
	v_readlane_b32 s72, v254, 20
	v_readlane_b32 s74, v254, 22
	v_readlane_b32 s75, v254, 23

; __device__ __forceinline__ void transpose_item(const float* W, int K, int N, bf16_t* WT, LAS float* scr, int item, int lane, int perm_cols) {
;     ...
;     for (int i = 0; i < 32; ++i) { const int kk = 2 * i + (lane >> 5); scr[kk * 33 + (lane & 31)] = W[(size_t)(k0 + kk) * N + n0 + (lane & 31)]; }
.LBB0_68:
	s_lshl_b32 s25, s22, 1
	s_lshl_b32 s28, s23, 1
	v_or_b32_e32 v123, s25, v3
	v_or_b32_e32 v170, s28, v4
	s_add_i32 s29, s25, 4
	s_add_i32 s41, s28, 4
	s_add_i32 s42, s25, 8
	s_add_i32 s43, s28, 8
	s_add_i32 s44, s25, 12
	s_add_i32 s45, s28, 12
	s_add_i32 s46, s25, 16
	s_add_i32 s47, s28, 16
	s_add_i32 s50, s25, 20
	s_add_i32 s51, s28, 20
	s_add_i32 s54, s25, 24
	s_add_i32 s55, s28, 24
	s_add_i32 s56, s25, 28
	s_add_i32 s57, s28, 28
	v_mad_i64_i32 v[126:127], s[26:27], v170, s39, v[16:17]
	v_mad_i64_i32 v[128:129], s[26:27], v123, s39, v[16:17]
	v_or_b32_e32 v123, s29, v3
	v_or_b32_e32 v170, s41, v4
	v_or_b32_e32 v171, s42, v3
	v_or_b32_e32 v125, s43, v4
	v_or_b32_e32 v140, s44, v3
	v_or_b32_e32 v138, s45, v4
	v_or_b32_e32 v144, s46, v3
	v_or_b32_e32 v142, s47, v4
	v_or_b32_e32 v148, s50, v3
	v_or_b32_e32 v146, s51, v4
	v_or_b32_e32 v152, s54, v3
	v_or_b32_e32 v150, s55, v4
	v_or_b32_e32 v156, s56, v3
	v_or_b32_e32 v154, s57, v4
	v_mad_i64_i32 v[130:131], s[26:27], v170, s39, v[16:17]
	v_mad_i64_i32 v[132:133], s[26:27], v123, s39, v[16:17]
	v_mad_i64_i32 v[134:135], s[26:27], v125, s39, v[16:17]
	v_mad_i64_i32 v[136:137], s[26:27], v171, s39, v[16:17]
	v_mad_i64_i32 v[138:139], s[26:27], v138, s39, v[16:17]
	v_mad_i64_i32 v[140:141], s[26:27], v140, s39, v[16:17]
	v_mad_i64_i32 v[142:143], s[26:27], v142, s39, v[16:17]
	v_mad_i64_i32 v[144:145], s[26:27], v144, s39, v[16:17]
	v_mad_i64_i32 v[146:147], s[26:27], v146, s39, v[16:17]
	v_mad_i64_i32 v[148:149], s[26:27], v148, s39, v[16:17]
	v_mad_i64_i32 v[150:151], s[26:27], v150, s39, v[16:17]
	v_mad_i64_i32 v[152:153], s[26:27], v152, s39, v[16:17]
	v_mad_i64_i32 v[154:155], s[26:27], v154, s39, v[16:17]
	v_mad_i64_i32 v[156:157], s[26:27], v156, s39, v[16:17]
	global_load_dword v123, v[126:127], off
	global_load_dword v170, v[128:129], off
	global_load_dword v171, v[130:131], off
	global_load_dword v125, v[132:133], off
	global_load_dword v158, v[134:135], off
	global_load_dword v159, v[136:137], off
	global_load_dword v160, v[138:139], off
	global_load_dword v161, v[140:141], off
	global_load_dword v162, v[142:143], off
	global_load_dword v163, v[144:145], off
	global_load_dword v164, v[146:147], off
	global_load_dword v165, v[148:149], off
	global_load_dword v166, v[150:151], off
	global_load_dword v167, v[152:153], off
	global_load_dword v168, v[154:155], off
	global_load_dword v169, v[156:157], off
	v_or_b32_e32 v128, s25, v1
	v_or_b32_e32 v126, s28, v2
	s_add_i32 s23, s23, 16
	s_add_i32 s22, s22, 16
	s_add_i32 s24, s24, -16
	v_mad_u64_u32 v[126:127], s[26:27], v126, s3, v[6:7]
	v_mad_u64_u32 v[128:129], s[26:27], v128, s3, v[6:7]
	v_or_b32_e32 v127, s29, v1
	v_or_b32_e32 v129, s41, v2
	v_or_b32_e32 v136, s42, v1
	v_or_b32_e32 v134, s43, v2
	v_or_b32_e32 v140, s44, v1
	v_or_b32_e32 v138, s45, v2
	v_or_b32_e32 v144, s46, v1
	v_or_b32_e32 v142, s47, v2
	v_or_b32_e32 v148, s50, v1
	v_or_b32_e32 v146, s51, v2
	v_or_b32_e32 v152, s54, v1
	v_or_b32_e32 v150, s55, v2
	v_or_b32_e32 v156, s56, v1
	v_or_b32_e32 v154, s57, v2
	s_cmp_lg_u32 s24, 0
	v_mad_u64_u32 v[130:131], s[26:27], v129, s3, v[6:7]
	v_mad_u64_u32 v[132:133], s[26:27], v127, s3, v[6:7]
	v_mad_u64_u32 v[134:135], s[26:27], v134, s3, v[6:7]
	v_mad_u64_u32 v[136:137], s[26:27], v136, s3, v[6:7]
	v_mad_u64_u32 v[138:139], s[26:27], v138, s3, v[6:7]
	v_mad_u64_u32 v[140:141], s[26:27], v140, s3, v[6:7]
	v_mad_u64_u32 v[142:143], s[26:27], v142, s3, v[6:7]
	v_mad_u64_u32 v[144:145], s[26:27], v144, s3, v[6:7]
	v_mad_u64_u32 v[146:147], s[26:27], v146, s3, v[6:7]
	v_mad_u64_u32 v[148:149], s[26:27], v148, s3, v[6:7]
	v_mad_u64_u32 v[150:151], s[26:27], v150, s3, v[6:7]
	v_mad_u64_u32 v[152:153], s[26:27], v152, s3, v[6:7]
	v_mad_u64_u32 v[154:155], s[26:27], v154, s3, v[6:7]
	v_mad_u64_u32 v[156:157], s[26:27], v156, s3, v[6:7]
	s_lshl_b32 s25, s22, 1
	s_lshl_b32 s28, s23, 1
	v_or_b32_e32 v9, s25, v3
	v_or_b32_e32 v13, s28, v4
	s_add_i32 s29, s25, 4
	s_add_i32 s41, s28, 4
	s_add_i32 s42, s25, 8
	s_add_i32 s43, s28, 8
	s_add_i32 s44, s25, 12
	s_add_i32 s45, s28, 12
	s_add_i32 s46, s25, 16
	s_add_i32 s47, s28, 16
	s_add_i32 s50, s25, 20
	s_add_i32 s51, s28, 20
	s_add_i32 s54, s25, 24
	s_add_i32 s55, s28, 24
	s_add_i32 s56, s25, 28
	s_add_i32 s57, s28, 28
	v_mad_i64_i32 v[32:33], s[26:27], v13, s39, v[16:17]
	v_mad_i64_i32 v[34:35], s[26:27], v9, s39, v[16:17]
	v_or_b32_e32 v9, s29, v3
	v_or_b32_e32 v13, s41, v4
	v_or_b32_e32 v15, s42, v3
	v_or_b32_e32 v31, s43, v4
	v_or_b32_e32 v46, s44, v3
	v_or_b32_e32 v44, s45, v4
	v_or_b32_e32 v50, s46, v3
	v_or_b32_e32 v48, s47, v4
	v_or_b32_e32 v54, s50, v3
	v_or_b32_e32 v52, s51, v4
	v_or_b32_e32 v58, s54, v3
	v_or_b32_e32 v56, s55, v4
	v_or_b32_e32 v62, s56, v3
	v_or_b32_e32 v60, s57, v4
	v_mad_i64_i32 v[36:37], s[26:27], v13, s39, v[16:17]
	v_mad_i64_i32 v[38:39], s[26:27], v9, s39, v[16:17]
	v_mad_i64_i32 v[40:41], s[26:27], v31, s39, v[16:17]
	v_mad_i64_i32 v[42:43], s[26:27], v15, s39, v[16:17]
	v_mad_i64_i32 v[44:45], s[26:27], v44, s39, v[16:17]
	v_mad_i64_i32 v[46:47], s[26:27], v46, s39, v[16:17]
	v_mad_i64_i32 v[48:49], s[26:27], v48, s39, v[16:17]
	v_mad_i64_i32 v[50:51], s[26:27], v50, s39, v[16:17]
	v_mad_i64_i32 v[52:53], s[26:27], v52, s39, v[16:17]
	v_mad_i64_i32 v[54:55], s[26:27], v54, s39, v[16:17]
	v_mad_i64_i32 v[56:57], s[26:27], v56, s39, v[16:17]
	v_mad_i64_i32 v[58:59], s[26:27], v58, s39, v[16:17]
	v_mad_i64_i32 v[60:61], s[26:27], v60, s39, v[16:17]
	v_mad_i64_i32 v[62:63], s[26:27], v62, s39, v[16:17]
	global_load_dword v9, v[32:33], off
	global_load_dword v13, v[34:35], off
	global_load_dword v15, v[36:37], off
	global_load_dword v31, v[38:39], off
; #define LAS __attribute__((address_space(3)))
; __device__ __forceinline__ unsigned cvt_pk_bf16(float lo, float hi) { f32x2 v = {lo, hi}; bf16x2_t b = __builtin_convertvector(v, bf16x2_t); return __builtin_bit_cast(unsigned, b); }
; __device__ __forceinline__ void transpose_item(const float* W, int K, int N, bf16_t* WT, LAS float* scr, int item, int lane, int perm_cols) {
;     ...
;     for (int i = 0; i < 32; ++i) { const int kk = 2 * i + (lane >> 5); scr[kk * 33 + (lane & 31)] = W[(size_t)(k0 + kk) * N + n0 + (lane & 31)]; }
;     asm volatile("s_waitcnt lgkmcnt(0)" ::: "memory");
;     const int c = lane & 7; const bool perm = n0 < perm_cols;
; #pragma unroll
;     for (int j = 0; j < 4; ++j) { const int n = (lane >> 3) + 8 * j; const int sn = perm ? ((n >> 1) + 16 * (n & 1)) : n; const LAS float* s = scr + (8 * c) * 33 + sn;
;         u32x4 o; o.x = cvt_pk_bf16(s[0 * 33], s[1 * 33]); o.y = cvt_pk_bf16(s[2 * 33], s[3 * 33]); o.z = cvt_pk_bf16(s[4 * 33], s[5 * 33]); o.w = cvt_pk_bf16(s[6 * 33], s[7 * 33]);
;         *(u32x4*)(WT + (size_t)(n0 + n) * K + k0 + 8 * c) = o; }
	global_load_dword v64, v[40:41], off
	global_load_dword v65, v[42:43], off
	global_load_dword v66, v[44:45], off
	global_load_dword v67, v[46:47], off
	global_load_dword v68, v[48:49], off
	global_load_dword v69, v[50:51], off
	global_load_dword v70, v[52:53], off
	global_load_dword v71, v[54:55], off
	global_load_dword v72, v[56:57], off
	global_load_dword v73, v[58:59], off
	global_load_dword v74, v[60:61], off
	global_load_dword v75, v[62:63], off
	v_or_b32_e32 v34, s25, v1
	v_or_b32_e32 v32, s28, v2
	s_add_i32 s23, s23, 16
	s_add_i32 s22, s22, 16
	s_add_i32 s24, s24, -16
	v_mad_u64_u32 v[32:33], s[26:27], v32, s3, v[6:7]
	v_mad_u64_u32 v[34:35], s[26:27], v34, s3, v[6:7]
	v_or_b32_e32 v33, s29, v1
	v_or_b32_e32 v35, s41, v2
	v_or_b32_e32 v42, s42, v1
	v_or_b32_e32 v40, s43, v2
	v_or_b32_e32 v46, s44, v1
	v_or_b32_e32 v44, s45, v2
	v_or_b32_e32 v50, s46, v1
	v_or_b32_e32 v48, s47, v2
	v_or_b32_e32 v54, s50, v1
	v_or_b32_e32 v52, s51, v2
	v_or_b32_e32 v58, s54, v1
	v_or_b32_e32 v56, s55, v2
	v_or_b32_e32 v62, s56, v1
	v_or_b32_e32 v60, s57, v2
	s_cmp_lg_u32 s24, 0
	v_mad_u64_u32 v[36:37], s[26:27], v35, s3, v[6:7]
	v_mad_u64_u32 v[38:39], s[26:27], v33, s3, v[6:7]
	v_mad_u64_u32 v[40:41], s[26:27], v40, s3, v[6:7]
	v_mad_u64_u32 v[42:43], s[26:27], v42, s3, v[6:7]
	v_mad_u64_u32 v[44:45], s[26:27], v44, s3, v[6:7]
	v_mad_u64_u32 v[46:47], s[26:27], v46, s3, v[6:7]
	v_mad_u64_u32 v[48:49], s[26:27], v48, s3, v[6:7]
	v_mad_u64_u32 v[50:51], s[26:27], v50, s3, v[6:7]
	v_mad_u64_u32 v[52:53], s[26:27], v52, s3, v[6:7]
	v_mad_u64_u32 v[54:55], s[26:27], v54, s3, v[6:7]
	v_mad_u64_u32 v[56:57], s[26:27], v56, s3, v[6:7]
	v_mad_u64_u32 v[58:59], s[26:27], v58, s3, v[6:7]
	v_mad_u64_u32 v[60:61], s[26:27], v60, s3, v[6:7]
	v_mad_u64_u32 v[62:63], s[26:27], v62, s3, v[6:7]
	s_waitcnt vmcnt(31)
	ds_write_b32 v126, v123
	s_waitcnt vmcnt(30)
	ds_write_b32 v128, v170
	s_waitcnt vmcnt(29)
	ds_write_b32 v130, v171
	s_waitcnt vmcnt(28)
	ds_write_b32 v132, v125
	s_waitcnt vmcnt(27)
	ds_write_b32 v134, v158
	s_waitcnt vmcnt(26)
	ds_write_b32 v136, v159
	s_waitcnt vmcnt(25)
	ds_write_b32 v138, v160
	s_waitcnt vmcnt(24)
	ds_write_b32 v140, v161
	s_waitcnt vmcnt(23)
	ds_write_b32 v142, v162
	s_waitcnt vmcnt(22)
	ds_write_b32 v144, v163
	s_waitcnt vmcnt(21)
	ds_write_b32 v146, v164
	s_waitcnt vmcnt(20)
	ds_write_b32 v148, v165
	s_waitcnt vmcnt(19)
	ds_write_b32 v150, v166
	s_waitcnt vmcnt(18)
	ds_write_b32 v152, v167
	s_waitcnt vmcnt(17)
	ds_write_b32 v154, v168
	s_waitcnt vmcnt(16)
	ds_write_b32 v156, v169
	s_waitcnt vmcnt(15)
	ds_write_b32 v32, v9
	s_waitcnt vmcnt(14)
	ds_write_b32 v34, v13
	s_waitcnt vmcnt(13)
	ds_write_b32 v36, v15
	s_waitcnt vmcnt(12)
	ds_write_b32 v38, v31
	s_waitcnt vmcnt(11)
	ds_write_b32 v40, v64
	s_waitcnt vmcnt(10)
	ds_write_b32 v42, v65
	s_waitcnt vmcnt(9)
	ds_write_b32 v44, v66
	s_waitcnt vmcnt(8)
	ds_write_b32 v46, v67
	s_waitcnt vmcnt(7)
	ds_write_b32 v48, v68
	s_waitcnt vmcnt(6)
	ds_write_b32 v50, v69
	s_waitcnt vmcnt(5)
	ds_write_b32 v52, v70
	s_waitcnt vmcnt(4)
	ds_write_b32 v54, v71
	s_waitcnt vmcnt(3)
	ds_write_b32 v56, v72
	s_waitcnt vmcnt(2)
	ds_write_b32 v58, v73
	s_waitcnt vmcnt(1)
	ds_write_b32 v60, v74
	s_waitcnt vmcnt(0)
	ds_write_b32 v62, v75
	v_cmp_gt_i16_e32 vcc, 64, v30
	v_mul_hi_i32_i24_e32 v17, 0x600000, v11
	v_mul_i32_i24_e32 v16, 0x600000, v11
	v_cndmask_b32_e32 v3, v18, v24, vcc
	v_lshl_add_u64 v[16:17], s[16:17], 0, v[16:17]
	s_waitcnt lgkmcnt(0)
	v_ashrrev_i32_e32 v15, 31, v14
	v_lshl_add_u32 v3, v3, 2, v19
	v_lshl_add_u64 v[14:15], v[14:15], 1, v[16:17]
	ds_read2_b32 v[16:17], v3 offset1:33
	ds_read2_b32 v[30:31], v3 offset0:66 offset1:99
	ds_read2_b32 v[32:33], v3 offset0:132 offset1:165
	ds_read2_b32 v[34:35], v3 offset0:198 offset1:231
	v_cndmask_b32_e32 v3, v21, v25, vcc
	v_mov_b32_e32 v11, v5
	v_lshl_add_u32 v3, v3, 2, v19
	v_lshl_add_u64 v[36:37], v[14:15], 0, v[10:11]
	s_waitcnt lgkmcnt(3)
	v_cvt_pk_bf16_f32 v14, v16, v17
	s_waitcnt lgkmcnt(2)
	v_cvt_pk_bf16_f32 v15, v30, v31
	s_waitcnt lgkmcnt(1)
	v_cvt_pk_bf16_f32 v16, v32, v33
	s_waitcnt lgkmcnt(0)
	v_cvt_pk_bf16_f32 v17, v34, v35
	v_or_b32_e32 v30, v12, v18
	ds_read2_b32 v[32:33], v3 offset1:33
	ds_read2_b32 v[34:35], v3 offset0:66 offset1:99
	ds_read2_b32 v[38:39], v3 offset0:132 offset1:165
	ds_read2_b32 v[40:41], v3 offset0:198 offset1:231
	v_ashrrev_i32_e32 v31, 31, v30
	v_lshlrev_b64 v[30:31], 11, v[30:31]
	v_lshl_add_u64 v[30:31], v[36:37], 0, v[30:31]
	v_cndmask_b32_e32 v3, v22, v26, vcc
	global_store_dwordx4 v[30:31], v[14:17], off
	v_lshl_add_u32 v3, v3, 2, v19
	v_or_b32_e32 v30, v12, v21
	s_waitcnt lgkmcnt(3)
	v_cvt_pk_bf16_f32 v14, v32, v33
	s_waitcnt lgkmcnt(2)
	v_cvt_pk_bf16_f32 v15, v34, v35
	s_waitcnt lgkmcnt(1)
	v_cvt_pk_bf16_f32 v16, v38, v39
	s_waitcnt lgkmcnt(0)
	v_cvt_pk_bf16_f32 v17, v40, v41
	ds_read2_b32 v[32:33], v3 offset1:33
	ds_read2_b32 v[34:35], v3 offset0:66 offset1:99
	ds_read2_b32 v[38:39], v3 offset0:132 offset1:165
	ds_read2_b32 v[40:41], v3 offset0:198 offset1:231
	v_ashrrev_i32_e32 v31, 31, v30
	v_lshlrev_b64 v[30:31], 11, v[30:31]
	v_lshl_add_u64 v[30:31], v[36:37], 0, v[30:31]
	v_cndmask_b32_e32 v3, v23, v27, vcc
	global_store_dwordx4 v[30:31], v[14:17], off
	v_lshl_add_u32 v3, v3, 2, v19
	v_or_b32_e32 v30, v12, v22
	s_waitcnt lgkmcnt(3)
	v_cvt_pk_bf16_f32 v14, v32, v33
	s_waitcnt lgkmcnt(2)
	v_cvt_pk_bf16_f32 v15, v34, v35
	s_waitcnt lgkmcnt(1)
	v_cvt_pk_bf16_f32 v16, v38, v39
	s_waitcnt lgkmcnt(0)
	v_cvt_pk_bf16_f32 v17, v40, v41
	ds_read2_b32 v[32:33], v3 offset1:33
	ds_read2_b32 v[34:35], v3 offset0:66 offset1:99
	ds_read2_b32 v[38:39], v3 offset0:132 offset1:165
	ds_read2_b32 v[40:41], v3 offset0:198 offset1:231
	v_ashrrev_i32_e32 v31, 31, v30
	v_or_b32_e32 v12, v12, v23
	v_lshlrev_b64 v[30:31], 11, v[30:31]
	v_ashrrev_i32_e32 v13, 31, v12
	v_lshl_add_u64 v[30:31], v[36:37], 0, v[30:31]
	v_lshlrev_b64 v[12:13], 11, v[12:13]
	global_store_dwordx4 v[30:31], v[14:17], off
	v_lshl_add_u64 v[12:13], v[36:37], 0, v[12:13]
	s_waitcnt lgkmcnt(3)
	v_cvt_pk_bf16_f32 v14, v32, v33
	s_waitcnt lgkmcnt(2)
	v_cvt_pk_bf16_f32 v15, v34, v35
	s_waitcnt lgkmcnt(1)
	v_cvt_pk_bf16_f32 v16, v38, v39
	s_waitcnt lgkmcnt(0)
	v_cvt_pk_bf16_f32 v17, v40, v41
	global_store_dwordx4 v[12:13], v[14:17], off
	s_waitcnt lgkmcnt(0)
	s_branch .LBB0_37
